# v37 + re-stagger barrier moved after next-unit scalar block (s32 flag), dropped compiler drain vmcnt(0) before mainloop in copies 2/3, grid barrier waiters poll cross-XCD generation directly (no per-X
# baseline (speedup 1.0000x reference)
; __device__ __forceinline__ unsigned xb_ld(unsigned* p)              { return __hip_atomic_load(p, __ATOMIC_RELAXED, __HIP_MEMORY_SCOPE_AGENT); }
; __device__ __forceinline__ unsigned xb_add(unsigned* p, unsigned v) { return __hip_atomic_fetch_add(p, v, __ATOMIC_RELAXED, __HIP_MEMORY_SCOPE_AGENT); }
; #define XB_SPIN(cond, bar) do { unsigned _sp = 0; while (cond) { __builtin_amdgcn_s_sleep(6); \
;     if ((++_sp & 255u) == 0u) { if (xb_ld(&(bar)[XB_TMO])) break; if (_sp > XB_SPIN_CAP) { atomicAdd(&(bar)[XB_TMO], 1u); break; } } } } while (0)
; __device__ __forceinline__ void xcd_barrier(const XcdBarrier& b) {
;     ...
;         const unsigned old = xb_add(&bar[XB_XSUB(b.x)], 1u);
;         const unsigned gen = old / nloc;
;         if (old + 1u == (gen + 1u) * nloc) {
;             __builtin_amdgcn_fence(__ATOMIC_RELEASE, "agent");
;             asm volatile("s_waitcnt vmcnt(0)" ::: "memory");
;             const unsigned og = xb_add(&bar[XB_TOP], 1u);
;             const unsigned tg = og / nx;
;             if (og + 1u == (tg + 1u) * nx) xb_add(&bar[XB_TOPGEN], 1u);
;             else XB_SPIN(xb_ld(&bar[XB_TOPGEN]) == tg, bar);
;             __builtin_amdgcn_fence(__ATOMIC_ACQUIRE, "agent");
;             xb_add(&bar[XB_XGEN(b.x)], 1u);
;             asm volatile("s_waitcnt vmcnt(0)" ::: "memory");
;         } else {
;             XB_SPIN(xb_ld(&bar[XB_XGEN(b.x)]) == gen, bar);
.LBB0_300:
	s_or_b64 exec, exec, s[8:9]
	v_cvt_f32_u32_e32 v5, v3
	s_waitcnt vmcnt(0)
	v_readfirstlane_b32 s2, v4
	v_sub_u32_e32 v4, 0, v3
	v_rcp_iflag_f32_e32 v5, v5
	v_add_u32_e32 v6, s2, v2
	v_mul_f32_e32 v5, 0x4f7ffffe, v5
	v_cvt_u32_f32_e32 v5, v5
	v_mul_lo_u32 v2, v4, v5
	v_mul_hi_u32 v2, v5, v2
	v_add_u32_e32 v2, v5, v2
	v_mul_hi_u32 v2, v6, v2
	v_mul_lo_u32 v4, v2, v3
	v_sub_u32_e32 v4, v6, v4
	v_add_u32_e32 v5, 1, v2
	v_cmp_ge_u32_e32 vcc, v4, v3
	s_nop 1
	v_cndmask_b32_e32 v2, v2, v5, vcc
	v_sub_u32_e32 v5, v4, v3
	v_cndmask_b32_e32 v4, v4, v5, vcc
	v_add_u32_e32 v5, 1, v2
	v_cmp_ge_u32_e32 vcc, v4, v3
	v_add_u32_e32 v4, 1, v6
	s_nop 0
	v_cndmask_b32_e32 v2, v2, v5, vcc
	v_mul_lo_u32 v5, v3, v2
	v_add_u32_e32 v3, v5, v3
	v_cmp_ne_u32_e32 vcc, v4, v3
	s_and_saveexec_b64 s[2:3], vcc
	s_xor_b64 s[6:7], exec, s[2:3]
	s_cbranch_execz .LBB0_314
	s_waitcnt lgkmcnt(0)
	v_readlane_b32 s10, v253, 6
	v_readlane_b32 s11, v253, 7
	v_mov_b32_e32 v1, 0
	s_add_u32 s10, s10, 0x3500
	s_addc_u32 s11, s11, 0
	global_load_dword v1, v1, s[10:11] sc1
	s_waitcnt vmcnt(0)
	v_cmp_eq_u32_e32 vcc, v1, v2
	s_and_saveexec_b64 s[8:9], vcc
	s_cbranch_execz .LBB0_313
	s_mov_b32 s2, 1
	s_mov_b64 s[12:13], 0
	v_mov_b32_e32 v1, 0
	s_branch .LBB0_304

; __device__ __forceinline__ unsigned xb_add(unsigned* p, unsigned v) { return __hip_atomic_fetch_add(p, v, __ATOMIC_RELAXED, __HIP_MEMORY_SCOPE_AGENT); }
; __device__ __forceinline__ void xcd_barrier(const XcdBarrier& b) {
;     ...
;             __builtin_amdgcn_fence(__ATOMIC_ACQUIRE, "agent");
;             xb_add(&bar[XB_XGEN(b.x)], 1u);
.LBB0_331:
	s_or_b64 exec, exec, s[6:7]
	s_mov_b64 s[6:7], exec
	v_mbcnt_lo_u32_b32 v1, s6, 0
	v_mbcnt_hi_u32_b32 v1, s7, v1
	v_cmp_eq_u32_e32 vcc, 0, v1
	s_waitcnt vmcnt(0)
	buffer_inv sc1
	s_and_saveexec_b64 s[8:9], vcc
	s_cbranch_execz .LBB0_333
	s_bcnt1_i32_b64 s2, s[6:7]
	v_mov_b32_e32 v1, 0x2000
	v_mov_b32_e32 v2, s2
.LBB0_333:
	s_or_b64 exec, exec, s[8:9]
	s_waitcnt vmcnt(0)

; #define PG8_STAGE(bufoff, gbase, voff) do { _Pragma("unroll") for (int _i = 0; _i < 2; ++_i) \
;         __builtin_amdgcn_global_load_lds((const unsigned*)((const char*)(gbase) + (voff)[_i]), (LAS unsigned*)(lds + (bufoff) + ldsw + _i * 8192), 16, 0, 0); } while (0)
; #define PG8_WAIT_V(n) asm volatile("s_waitcnt vmcnt(" #n ")" ::: "memory")
; #define PG8_BAR __builtin_amdgcn_s_barrier()
; __device__ __forceinline__ void gemm_phase(LAS unsigned char* lds, const Gemm g, const StaticOrder& S, const LAS Epi* Ep, const int tid) {
;     ...
;     PG8_STAGE(PG8_SB(0, 0), cB, voffB); PG8_STAGE(PG8_SB(0, 1), cB + hstepB, voffB); PG8_STAGE(PG8_SA(0, 0), cA, voffA); PG8_STAGE(PG8_SA(0, 1), cA + hstepA, voffA);
;     if (wr == 1) PG8_BAR;
;     PG8_WAIT_V(2); PG8_BAR;
;     PG8_STAGE(PG8_SB(1, 0), cB + kstep, voffB); PG8_STAGE(PG8_SA(1, 0), cA + kstep, voffA); PG8_STAGE(PG8_SB(1, 1), cB + hstepB + kstep, voffB);
;     PG8_WAIT_V(6); PG8_BAR;
.LBB0_397:
	s_add_i32 m0, s78, 0x18000
	v_lshl_add_u64 v[12:13], v[12:13], 0, s[88:89]
	s_waitcnt vmcnt(2)
	s_barrier
	global_load_lds_dwordx4 v[12:13], off
	v_lshl_add_u64 v[8:9], v[8:9], 0, s[88:89]
	s_add_i32 m0, s78, 0x1a000
	s_add_i32 s59, s78, 0x8000
	global_load_lds_dwordx4 v[8:9], off
	v_lshl_add_u64 v[8:9], v[10:11], 0, s[88:89]
	s_mov_b32 m0, s59
	s_add_i32 s60, s78, 0xa000
	global_load_lds_dwordx4 v[8:9], off
	v_lshl_add_u64 v[8:9], v[14:15], 0, s[88:89]
	s_mov_b32 m0, s60
	v_lshl_add_u64 v[6:7], v[6:7], 0, s[88:89]
	global_load_lds_dwordx4 v[8:9], off
	s_add_i32 m0, s78, 0x1c000
	v_lshl_add_u64 v[4:5], v[4:5], 0, s[88:89]
	global_load_lds_dwordx4 v[6:7], off
	s_add_i32 m0, s78, 0x1e000
	s_lshl_b32 s8, s8, 5
	global_load_lds_dwordx4 v[4:5], off
	s_lshr_b32 s61, s35, 6
	s_and_b32 s11, s8, 0x60
	v_and_b32_e32 v232, 15, v16
	v_and_b32_e32 v4, 48, v16
	v_lshlrev_b32_e32 v5, 2, v16
	s_lshl_b32 s35, s9, 6
	s_lshl_b32 s9, s9, 13
	s_lshl_b32 s8, s11, 7
	s_add_i32 s66, s61, -2
	v_lshl_or_b32 v4, v232, 6, v4
	v_and_b32_e32 v5, 32, v5
	s_cmpk_lt_u32 s10, 0x100
	v_bitop3_b32 v6, v4, s9, v5 bitop3:0xde
	v_bitop3_b32 v233, s8, v4, v5 bitop3:0xf6
	s_cselect_b64 s[8:9], -1, 0
	s_lshl_b32 s80, s3, 2
	v_cvt_f32_u32_e32 v7, s80
	v_and_b32_e32 v4, 63, v16
	s_and_b32 s10, s10, 0x7ffffc0
	v_cmp_gt_u32_e64 s[40:41], 16, v4
	v_or_b32_e32 v4, s10, v4
	v_lshlrev_b32_e32 v234, 5, v4
	v_rcp_iflag_f32_e32 v4, v7
	v_add_u32_e32 v2, v21, v2
	s_lshl_b32 s81, s3, 3
	s_sub_i32 s3, 0, s80
	v_mul_f32_e32 v4, 0x4f7ffffe, v4
	v_cvt_u32_f32_e32 v4, v4
	v_add_lshl_u32 v2, v2, v17, 1
	v_lshrrev_b32_e32 v5, 1, v16
	s_waitcnt vmcnt(6)
	v_readfirstlane_b32 s10, v4
	s_mul_i32 s3, s3, s10
	v_lshl_add_u64 v[206:207], s[86:87], 0, v[2:3]
	v_add_u32_e32 v2, v20, v18
	v_and_or_b32 v204, v5, 24, s11
	s_mul_hi_u32 s3, s10, s3
	v_add_lshl_u32 v2, v2, v19, 1
	v_cmp_lt_u32_e64 s[42:43], 12, v232
	v_add_u32_e32 v202, -13, v232
	v_mov_b32_e32 v203, v3
	v_cmp_gt_u32_e64 s[44:45], 16, v204
	s_mov_b32 s97, s87
	s_mov_b32 s68, 0
	s_add_i32 s69, s10, s3
	v_lshl_add_u64 v[208:209], s[86:87], 0, v[2:3]
	s_mov_b32 s70, -1
	v_add_u32_e32 v235, 0, v6
	s_barrier
	s_mov_b32 s32, 0
	s_branch .LBB0_400

; #define PG8_STAGE(bufoff, gbase, voff) do { _Pragma("unroll") for (int _i = 0; _i < 2; ++_i) \
;         __builtin_amdgcn_global_load_lds((const unsigned*)((const char*)(gbase) + (voff)[_i]), (LAS unsigned*)(lds + (bufoff) + ldsw + _i * 8192), 16, 0, 0); } while (0)
; #define PG8_LDA(dst, b, h) do { _Pragma("unroll") for (int m = 0; m < 4; ++m) _Pragma("unroll") for (int k = 0; k < 2; ++k) dst[m][k] = *(const LAS bf16x8*)(lds + PG8_SA(b, h) + aoff + m * 2048 + k * 1024); } while (0)
; #define PG8_LDB(dst, b, h) do { _Pragma("unroll") for (int n = 0; n < 2; ++n) _Pragma("unroll") for (int k = 0; k < 2; ++k) dst[n][k] = *(const LAS bf16x8*)(lds + PG8_SB(b, h) + boff + n * 2048 + k * 1024); } while (0)
; #define PG8_MMA(ai, bj, At, Bt) do { __builtin_amdgcn_s_setprio(1); _Pragma("unroll") for (int m = 0; m < 4; ++m) _Pragma("unroll") for (int n = 0; n < 2; ++n) _Pragma("unroll") for (int k = 0; k < 2; ++k) \
;         acc[ai][bj][m][n] = __builtin_amdgcn_mfma_f32_16x16x32_bf16(Bt[n][k], At[m][k], acc[ai][bj][m][n], 0, 0, 0); __builtin_amdgcn_s_setprio(0); } while (0)
; #define PG8_WAIT_V(n) asm volatile("s_waitcnt vmcnt(" #n ")" ::: "memory")
; #define PG8_WAIT_L(n) asm volatile("s_waitcnt lgkmcnt(" #n ")" ::: "memory")
; __device__ __forceinline__ void gemm_phase(LAS unsigned char* lds, const Gemm g, const StaticOrder& S, const LAS Epi* Ep, const int tid) {
;     ...
;         const bool has_next = S.next(ui + 1, nxt);
;         const char* nA = has_next ? (const char*)g.A + (size_t)nxt.pm * tstepA : cA; const char* nB = has_next ? (const char*)g.Bt + (size_t)nxt.pn * tstepB : cB;
;         for (int t = 0; t < nt; t += 2) {
;             const bool last = (t == nt - 2);
;             const char* a1 = cA + (size_t)(t + 1) * kstep;
;             const char* a2 = last ? nA : cA + (size_t)(t + 2) * kstep; const char* b2 = last ? nB : cB + (size_t)(t + 2) * kstep;
;             const char* a3 = a2 + kstep; const char* b3 = b2 + kstep;
;             PG8_LDB(B0, 0, 0); PG8_LDB(B1, 0, 1); PG8_SCHED; PG8_LDA(At, 0, 0); PG8_STAGE(PG8_SA(1, 1), a1 + hstepA, voffA);
;             PG8_WAIT_V(8); PG8_WAIT_L(0); PG8_BAR; PG8_MMA(0, 0, At, B0); PG8_MMA(0, 1, At, B1); PG8_BAR; PG8_SCHED;
;             PG8_LDA(At, 0, 1); PG8_STAGE(PG8_SB(0, 0), b2, voffB); PG8_STAGE(PG8_SB(0, 1), b2 + hstepB, voffB); PG8_STAGE(PG8_SA(0, 0), a2, voffA);
;     ...
;         if (wr == 1) PG8_BAR;
.LBB0_406:
	s_add_u32 s0, s0, 0x80
	s_addc_u32 s1, s1, 0
	s_add_u32 s3, s14, 0x100
	s_addc_u32 s16, s15, 0
	s_mov_b32 s14, 0
	s_cmp_eq_u32 s32, 0
	s_cbranch_scc1 .Lstag1_skip
	s_barrier
.Lstag1_skip:
	s_add_i32 s17, s14, 2
	s_add_u32 s18, s0, 0x80
	s_addc_u32 s15, s1, 0
	s_add_i32 s20, 0, 0x10000
	s_cmp_eq_u32 s66, s14
	s_cselect_b32 s15, s11, s15
	s_cselect_b32 s14, s10, s18
	v_add_u32_e32 v2, s20, v233
	s_cselect_b32 s19, s13, s16
	s_cselect_b32 s18, s12, s3
	s_add_i32 s21, 0, 0x14000
	s_waitcnt lgkmcnt(0)
	ds_read_b128 v[132:135], v2
	ds_read_b128 v[136:139], v2 offset:1024
	ds_read_b128 v[140:143], v2 offset:2048
	ds_read_b128 v[144:147], v2 offset:3072
	v_add_u32_e32 v2, s21, v233
	ds_read_b128 v[148:151], v2
	ds_read_b128 v[152:155], v2 offset:1024
	ds_read_b128 v[156:159], v2 offset:2048
	ds_read_b128 v[160:163], v2 offset:3072
	v_lshl_add_u64 v[210:211], s[0:1], 0, v[206:207]
	s_add_i32 m0, s78, 0xc000
	ds_read_b128 v[164:167], v235
	ds_read_b128 v[168:171], v235 offset:1024
	ds_read_b128 v[172:175], v235 offset:2048
	ds_read_b128 v[176:179], v235 offset:3072
	ds_read_b128 v[180:183], v235 offset:4096
	ds_read_b128 v[184:187], v235 offset:5120
	ds_read_b128 v[188:191], v235 offset:6144
	ds_read_b128 v[192:195], v235 offset:7168
	global_load_lds_dwordx4 v[210:211], off
	v_lshl_add_u64 v[210:211], s[0:1], 0, v[208:209]
	s_add_i32 m0, s78, 0xe000
	s_nop 0
	global_load_lds_dwordx4 v[210:211], off
	s_waitcnt vmcnt(8)
	s_waitcnt lgkmcnt(0)
	s_barrier
	s_setprio 1
	s_waitcnt lgkmcnt(0)
	v_mfma_f32_16x16x32_bf16 v[128:131], v[132:135], v[164:167], 0
	v_mfma_f32_16x16x32_bf16 v[120:123], v[140:143], v[164:167], 0
	v_mfma_f32_16x16x32_bf16 v[112:115], v[132:135], v[172:175], 0
	v_mfma_f32_16x16x32_bf16 v[104:107], v[140:143], v[172:175], 0
	v_mfma_f32_16x16x32_bf16 v[96:99], v[132:135], v[180:183], 0
	v_mfma_f32_16x16x32_bf16 v[88:91], v[140:143], v[180:183], 0
	v_mfma_f32_16x16x32_bf16 v[80:83], v[132:135], v[188:191], 0
	v_mfma_f32_16x16x32_bf16 v[72:75], v[140:143], v[188:191], 0
	v_mfma_f32_16x16x32_bf16 v[128:131], v[136:139], v[168:171], v[128:131]
	v_mfma_f32_16x16x32_bf16 v[120:123], v[144:147], v[168:171], v[120:123]
	v_mfma_f32_16x16x32_bf16 v[112:115], v[136:139], v[176:179], v[112:115]
	v_mfma_f32_16x16x32_bf16 v[104:107], v[144:147], v[176:179], v[104:107]
	v_mfma_f32_16x16x32_bf16 v[96:99], v[136:139], v[184:187], v[96:99]
	v_mfma_f32_16x16x32_bf16 v[88:91], v[144:147], v[184:187], v[88:91]
	v_mfma_f32_16x16x32_bf16 v[80:83], v[136:139], v[192:195], v[80:83]
	v_mfma_f32_16x16x32_bf16 v[72:75], v[144:147], v[192:195], v[72:75]
	s_setprio 0
	s_setprio 1
	v_mfma_f32_16x16x32_bf16 v[124:127], v[148:151], v[164:167], 0
	v_mfma_f32_16x16x32_bf16 v[116:119], v[156:159], v[164:167], 0
	v_mfma_f32_16x16x32_bf16 v[108:111], v[148:151], v[172:175], 0
	v_mfma_f32_16x16x32_bf16 v[100:103], v[156:159], v[172:175], 0
	v_mfma_f32_16x16x32_bf16 v[92:95], v[148:151], v[180:183], 0
	v_mfma_f32_16x16x32_bf16 v[84:87], v[156:159], v[180:183], 0
	v_mfma_f32_16x16x32_bf16 v[76:79], v[148:151], v[188:191], 0
	v_mfma_f32_16x16x32_bf16 v[68:71], v[156:159], v[188:191], 0
	v_mfma_f32_16x16x32_bf16 v[124:127], v[152:155], v[168:171], v[124:127]
	v_mfma_f32_16x16x32_bf16 v[116:119], v[160:163], v[168:171], v[116:119]
	v_mfma_f32_16x16x32_bf16 v[108:111], v[152:155], v[176:179], v[108:111]
	v_mfma_f32_16x16x32_bf16 v[100:103], v[160:163], v[176:179], v[100:103]
	v_mfma_f32_16x16x32_bf16 v[92:95], v[152:155], v[184:187], v[92:95]
	v_mfma_f32_16x16x32_bf16 v[84:87], v[160:163], v[184:187], v[84:87]
	v_mfma_f32_16x16x32_bf16 v[76:79], v[152:155], v[192:195], v[76:79]
	v_mfma_f32_16x16x32_bf16 v[68:71], v[160:163], v[192:195], v[68:71]
	s_setprio 0
	s_barrier
	s_add_i32 s20, s20, s85
	v_lshl_add_u64 v[210:211], s[18:19], 0, v[196:197]
	s_mov_b32 m0, s20
	ds_read_b128 v[164:167], v235 offset:16384
	ds_read_b128 v[168:171], v235 offset:17408
	ds_read_b128 v[172:175], v235 offset:18432
	ds_read_b128 v[176:179], v235 offset:19456
	ds_read_b128 v[180:183], v235 offset:20480
	ds_read_b128 v[184:187], v235 offset:21504
	ds_read_b128 v[188:191], v235 offset:22528
	ds_read_b128 v[192:195], v235 offset:23552
	global_load_lds_dwordx4 v[210:211], off
	s_add_i32 m0, s20, 0x2000
	v_lshl_add_u64 v[212:213], s[18:19], 0, v[200:201]
	s_add_u32 s18, s18, s39
	s_addc_u32 s19, s19, 0
	s_add_i32 s20, s21, s85
	global_load_lds_dwordx4 v[212:213], off
	v_lshl_add_u64 v[214:215], s[18:19], 0, v[196:197]
	s_mov_b32 m0, s20
	v_lshl_add_u64 v[216:217], s[18:19], 0, v[200:201]
	global_load_lds_dwordx4 v[214:215], off
	s_add_i32 m0, s20, 0x2000
	v_lshl_add_u64 v[218:219], s[14:15], 0, v[0:1]
	global_load_lds_dwordx4 v[216:217], off
	s_mov_b32 m0, s78
	v_lshl_add_u64 v[220:221], s[14:15], 0, v[198:199]
	global_load_lds_dwordx4 v[218:219], off
	s_mov_b32 m0, s56
	s_nop 0
	global_load_lds_dwordx4 v[220:221], off
	s_waitcnt vmcnt(8)
	s_waitcnt lgkmcnt(0)
	s_barrier
; #define PG8_STAGE(bufoff, gbase, voff) do { _Pragma("unroll") for (int _i = 0; _i < 2; ++_i) \
;         __builtin_amdgcn_global_load_lds((const unsigned*)((const char*)(gbase) + (voff)[_i]), (LAS unsigned*)(lds + (bufoff) + ldsw + _i * 8192), 16, 0, 0); } while (0)
; #define PG8_LDA(dst, b, h) do { _Pragma("unroll") for (int m = 0; m < 4; ++m) _Pragma("unroll") for (int k = 0; k < 2; ++k) dst[m][k] = *(const LAS bf16x8*)(lds + PG8_SA(b, h) + aoff + m * 2048 + k * 1024); } while (0)
; #define PG8_LDB(dst, b, h) do { _Pragma("unroll") for (int n = 0; n < 2; ++n) _Pragma("unroll") for (int k = 0; k < 2; ++k) dst[n][k] = *(const LAS bf16x8*)(lds + PG8_SB(b, h) + boff + n * 2048 + k * 1024); } while (0)
; #define PG8_MMA(ai, bj, At, Bt) do { __builtin_amdgcn_s_setprio(1); _Pragma("unroll") for (int m = 0; m < 4; ++m) _Pragma("unroll") for (int n = 0; n < 2; ++n) _Pragma("unroll") for (int k = 0; k < 2; ++k) \
;         acc[ai][bj][m][n] = __builtin_amdgcn_mfma_f32_16x16x32_bf16(Bt[n][k], At[m][k], acc[ai][bj][m][n], 0, 0, 0); __builtin_amdgcn_s_setprio(0); } while (0)
; #define PG8_WAIT_V(n) asm volatile("s_waitcnt vmcnt(" #n ")" ::: "memory")
; #define PG8_WAIT_L(n) asm volatile("s_waitcnt lgkmcnt(" #n ")" ::: "memory")
; #define PG8_BAR __builtin_amdgcn_s_barrier()
; #define PG8_SCHED __builtin_amdgcn_sched_barrier(0)
; __device__ __forceinline__ void gemm_phase(LAS unsigned char* lds, const Gemm g, const StaticOrder& S, const LAS Epi* Ep, const int tid) {
;     ...
;             PG8_WAIT_V(8); PG8_WAIT_L(0); PG8_BAR; PG8_MMA(1, 0, At, B0); PG8_MMA(1, 1, At, B1); PG8_BAR; PG8_SCHED;
;             PG8_LDB(B0, 1, 0); PG8_LDB(B1, 1, 1); PG8_SCHED; PG8_LDA(At, 1, 0); PG8_STAGE(PG8_SA(0, 1), a2 + hstepA, voffA);
;             PG8_WAIT_V(8); PG8_WAIT_L(0); PG8_BAR; PG8_MMA(0, 0, At, B0); PG8_MMA(0, 1, At, B1); PG8_BAR; PG8_SCHED;
	s_setprio 1
	s_waitcnt lgkmcnt(0)
	v_mfma_f32_16x16x32_bf16 v[64:67], v[132:135], v[164:167], 0
	v_mfma_f32_16x16x32_bf16 v[56:59], v[140:143], v[164:167], 0
	v_mfma_f32_16x16x32_bf16 v[48:51], v[132:135], v[172:175], 0
	v_mfma_f32_16x16x32_bf16 v[40:43], v[140:143], v[172:175], 0
	v_mfma_f32_16x16x32_bf16 v[32:35], v[132:135], v[180:183], 0
	v_mfma_f32_16x16x32_bf16 v[24:27], v[140:143], v[180:183], 0
	v_mfma_f32_16x16x32_bf16 v[16:19], v[132:135], v[188:191], 0
	v_mfma_f32_16x16x32_bf16 v[8:11], v[140:143], v[188:191], 0
	v_mfma_f32_16x16x32_bf16 v[64:67], v[136:139], v[168:171], v[64:67]
	v_mfma_f32_16x16x32_bf16 v[56:59], v[144:147], v[168:171], v[56:59]
	v_mfma_f32_16x16x32_bf16 v[48:51], v[136:139], v[176:179], v[48:51]
	v_mfma_f32_16x16x32_bf16 v[40:43], v[144:147], v[176:179], v[40:43]
	v_mfma_f32_16x16x32_bf16 v[32:35], v[136:139], v[184:187], v[32:35]
	v_mfma_f32_16x16x32_bf16 v[24:27], v[144:147], v[184:187], v[24:27]
	v_mfma_f32_16x16x32_bf16 v[16:19], v[136:139], v[192:195], v[16:19]
	v_mfma_f32_16x16x32_bf16 v[8:11], v[144:147], v[192:195], v[8:11]
	s_setprio 0
	s_setprio 1
	v_mfma_f32_16x16x32_bf16 v[60:63], v[148:151], v[164:167], 0
	v_mfma_f32_16x16x32_bf16 v[52:55], v[156:159], v[164:167], 0
	v_mfma_f32_16x16x32_bf16 v[44:47], v[148:151], v[172:175], 0
	v_mfma_f32_16x16x32_bf16 v[36:39], v[156:159], v[172:175], 0
	v_mfma_f32_16x16x32_bf16 v[28:31], v[148:151], v[180:183], 0
	v_mfma_f32_16x16x32_bf16 v[20:23], v[156:159], v[180:183], 0
	v_mfma_f32_16x16x32_bf16 v[12:15], v[148:151], v[188:191], 0
	v_mfma_f32_16x16x32_bf16 v[4:7], v[156:159], v[188:191], 0
	v_mfma_f32_16x16x32_bf16 v[60:63], v[152:155], v[168:171], v[60:63]
	v_mfma_f32_16x16x32_bf16 v[52:55], v[160:163], v[168:171], v[52:55]
	v_mfma_f32_16x16x32_bf16 v[44:47], v[152:155], v[176:179], v[44:47]
	v_mfma_f32_16x16x32_bf16 v[36:39], v[160:163], v[176:179], v[36:39]
	v_mfma_f32_16x16x32_bf16 v[28:31], v[152:155], v[184:187], v[28:31]
	v_mfma_f32_16x16x32_bf16 v[20:23], v[160:163], v[184:187], v[20:23]
	v_mfma_f32_16x16x32_bf16 v[12:15], v[152:155], v[192:195], v[12:15]
	v_mfma_f32_16x16x32_bf16 v[4:7], v[160:163], v[192:195], v[4:7]
	s_setprio 0
	s_barrier
	s_add_i32 s18, 0, 0x18000
	v_add_u32_e32 v2, s18, v233
	s_add_i32 s19, 0, 0x1c000
	ds_read_b128 v[132:135], v2
	ds_read_b128 v[136:139], v2 offset:1024
	ds_read_b128 v[140:143], v2 offset:2048
	ds_read_b128 v[144:147], v2 offset:3072
	v_add_u32_e32 v2, s19, v233
	ds_read_b128 v[148:151], v2
	ds_read_b128 v[152:155], v2 offset:1024
	ds_read_b128 v[156:159], v2 offset:2048
	ds_read_b128 v[160:163], v2 offset:3072
	s_add_u32 s14, s14, s86
	s_addc_u32 s15, s15, 0
	s_mov_b32 m0, s57
	v_lshl_add_u64 v[222:223], s[14:15], 0, v[0:1]
	ds_read_b128 v[164:167], v235 offset:32768
	ds_read_b128 v[168:171], v235 offset:33792
	ds_read_b128 v[172:175], v235 offset:34816
	ds_read_b128 v[176:179], v235 offset:35840
	ds_read_b128 v[180:183], v235 offset:36864
	ds_read_b128 v[184:187], v235 offset:37888
	ds_read_b128 v[188:191], v235 offset:38912
	ds_read_b128 v[192:195], v235 offset:39936
	global_load_lds_dwordx4 v[222:223], off
	v_lshl_add_u64 v[222:223], s[14:15], 0, v[198:199]
	s_mov_b32 m0, s58
	s_nop 0
	global_load_lds_dwordx4 v[222:223], off
	s_waitcnt vmcnt(8)
	s_waitcnt lgkmcnt(0)
	s_barrier
	s_setprio 1
	s_waitcnt lgkmcnt(0)
	v_mfma_f32_16x16x32_bf16 v[128:131], v[132:135], v[164:167], v[128:131]
	v_mfma_f32_16x16x32_bf16 v[120:123], v[140:143], v[164:167], v[120:123]
	v_mfma_f32_16x16x32_bf16 v[112:115], v[132:135], v[172:175], v[112:115]
	v_mfma_f32_16x16x32_bf16 v[104:107], v[140:143], v[172:175], v[104:107]
	v_mfma_f32_16x16x32_bf16 v[96:99], v[132:135], v[180:183], v[96:99]
	v_mfma_f32_16x16x32_bf16 v[88:91], v[140:143], v[180:183], v[88:91]
	v_mfma_f32_16x16x32_bf16 v[80:83], v[132:135], v[188:191], v[80:83]
	v_mfma_f32_16x16x32_bf16 v[72:75], v[140:143], v[188:191], v[72:75]
	v_mfma_f32_16x16x32_bf16 v[128:131], v[136:139], v[168:171], v[128:131]
	v_mfma_f32_16x16x32_bf16 v[120:123], v[144:147], v[168:171], v[120:123]
	v_mfma_f32_16x16x32_bf16 v[112:115], v[136:139], v[176:179], v[112:115]
	v_mfma_f32_16x16x32_bf16 v[104:107], v[144:147], v[176:179], v[104:107]
	v_mfma_f32_16x16x32_bf16 v[96:99], v[136:139], v[184:187], v[96:99]
	v_mfma_f32_16x16x32_bf16 v[88:91], v[144:147], v[184:187], v[88:91]
	v_mfma_f32_16x16x32_bf16 v[80:83], v[136:139], v[192:195], v[80:83]
	v_mfma_f32_16x16x32_bf16 v[72:75], v[144:147], v[192:195], v[72:75]
	s_setprio 0
	s_setprio 1
	v_mfma_f32_16x16x32_bf16 v[124:127], v[148:151], v[164:167], v[124:127]
	v_mfma_f32_16x16x32_bf16 v[116:119], v[156:159], v[164:167], v[116:119]
	v_mfma_f32_16x16x32_bf16 v[108:111], v[148:151], v[172:175], v[108:111]
	v_mfma_f32_16x16x32_bf16 v[100:103], v[156:159], v[172:175], v[100:103]
	v_mfma_f32_16x16x32_bf16 v[92:95], v[148:151], v[180:183], v[92:95]
	v_mfma_f32_16x16x32_bf16 v[84:87], v[156:159], v[180:183], v[84:87]
	v_mfma_f32_16x16x32_bf16 v[76:79], v[148:151], v[188:191], v[76:79]
	v_mfma_f32_16x16x32_bf16 v[68:71], v[156:159], v[188:191], v[68:71]
	v_mfma_f32_16x16x32_bf16 v[124:127], v[152:155], v[168:171], v[124:127]
	v_mfma_f32_16x16x32_bf16 v[116:119], v[160:163], v[168:171], v[116:119]
	v_mfma_f32_16x16x32_bf16 v[108:111], v[152:155], v[176:179], v[108:111]
	v_mfma_f32_16x16x32_bf16 v[100:103], v[160:163], v[176:179], v[100:103]
	v_mfma_f32_16x16x32_bf16 v[92:95], v[152:155], v[184:187], v[92:95]
	v_mfma_f32_16x16x32_bf16 v[84:87], v[160:163], v[184:187], v[84:87]
	v_mfma_f32_16x16x32_bf16 v[76:79], v[152:155], v[192:195], v[76:79]
	v_mfma_f32_16x16x32_bf16 v[68:71], v[160:163], v[192:195], v[68:71]
	s_setprio 0
	s_barrier
; #define PG8_STAGE(bufoff, gbase, voff) do { _Pragma("unroll") for (int _i = 0; _i < 2; ++_i) \
;         __builtin_amdgcn_global_load_lds((const unsigned*)((const char*)(gbase) + (voff)[_i]), (LAS unsigned*)(lds + (bufoff) + ldsw + _i * 8192), 16, 0, 0); } while (0)
; #define PG8_LDA(dst, b, h) do { _Pragma("unroll") for (int m = 0; m < 4; ++m) _Pragma("unroll") for (int k = 0; k < 2; ++k) dst[m][k] = *(const LAS bf16x8*)(lds + PG8_SA(b, h) + aoff + m * 2048 + k * 1024); } while (0)
; #define PG8_MMA(ai, bj, At, Bt) do { __builtin_amdgcn_s_setprio(1); _Pragma("unroll") for (int m = 0; m < 4; ++m) _Pragma("unroll") for (int n = 0; n < 2; ++n) _Pragma("unroll") for (int k = 0; k < 2; ++k) \
;         acc[ai][bj][m][n] = __builtin_amdgcn_mfma_f32_16x16x32_bf16(Bt[n][k], At[m][k], acc[ai][bj][m][n], 0, 0, 0); __builtin_amdgcn_s_setprio(0); } while (0)
; #define PG8_WAIT_V(n) asm volatile("s_waitcnt vmcnt(" #n ")" ::: "memory")
; #define PG8_WAIT_L(n) asm volatile("s_waitcnt lgkmcnt(" #n ")" ::: "memory")
; #define PG8_BAR __builtin_amdgcn_s_barrier()
; #define PG8_SCHED __builtin_amdgcn_sched_barrier(0)
; __device__ __forceinline__ void gemm_phase(LAS unsigned char* lds, const Gemm g, const StaticOrder& S, const LAS Epi* Ep, const int tid) {
;     ...
;             PG8_LDA(At, 1, 1); PG8_STAGE(PG8_SB(1, 0), b3, voffB); PG8_STAGE(PG8_SB(1, 1), b3 + hstepB, voffB); PG8_STAGE(PG8_SA(1, 0), a3, voffA);
;             PG8_WAIT_V(8); PG8_WAIT_L(0); PG8_BAR; PG8_MMA(1, 0, At, B0); PG8_MMA(1, 1, At, B1); PG8_BAR; PG8_SCHED;
;         }
	s_add_i32 s14, s18, s85
	v_lshl_add_u64 v[210:211], v[210:211], 0, s[88:89]
	s_mov_b32 m0, s14
	ds_read_b128 v[164:167], v235 offset:49152
	ds_read_b128 v[168:171], v235 offset:50176
	ds_read_b128 v[172:175], v235 offset:51200
	ds_read_b128 v[176:179], v235 offset:52224
	ds_read_b128 v[180:183], v235 offset:53248
	ds_read_b128 v[184:187], v235 offset:54272
	ds_read_b128 v[188:191], v235 offset:55296
	ds_read_b128 v[192:195], v235 offset:56320
	global_load_lds_dwordx4 v[210:211], off
	v_lshl_add_u64 v[210:211], v[212:213], 0, s[88:89]
	s_add_i32 m0, s14, 0x2000
	s_add_i32 s14, s19, s85
	global_load_lds_dwordx4 v[210:211], off
	v_lshl_add_u64 v[210:211], v[214:215], 0, s[88:89]
	s_mov_b32 m0, s14
	s_nop 0
	global_load_lds_dwordx4 v[210:211], off
	v_lshl_add_u64 v[210:211], v[216:217], 0, s[88:89]
	s_add_i32 m0, s14, 0x2000
	s_nop 0
	global_load_lds_dwordx4 v[210:211], off
	v_lshl_add_u64 v[210:211], v[218:219], 0, s[88:89]
	s_mov_b32 m0, s59
	s_nop 0
	global_load_lds_dwordx4 v[210:211], off
	v_lshl_add_u64 v[210:211], v[220:221], 0, s[88:89]
	s_mov_b32 m0, s60
	s_nop 0
	global_load_lds_dwordx4 v[210:211], off
	s_waitcnt vmcnt(8)
	s_waitcnt lgkmcnt(0)
	s_barrier
	s_setprio 1
	s_waitcnt lgkmcnt(0)
	v_mfma_f32_16x16x32_bf16 v[64:67], v[132:135], v[164:167], v[64:67]
	v_mfma_f32_16x16x32_bf16 v[56:59], v[140:143], v[164:167], v[56:59]
	v_mfma_f32_16x16x32_bf16 v[48:51], v[132:135], v[172:175], v[48:51]
	v_mfma_f32_16x16x32_bf16 v[40:43], v[140:143], v[172:175], v[40:43]
	v_mfma_f32_16x16x32_bf16 v[32:35], v[132:135], v[180:183], v[32:35]
	v_mfma_f32_16x16x32_bf16 v[24:27], v[140:143], v[180:183], v[24:27]
	v_mfma_f32_16x16x32_bf16 v[16:19], v[132:135], v[188:191], v[16:19]
	v_mfma_f32_16x16x32_bf16 v[8:11], v[140:143], v[188:191], v[8:11]
	v_mfma_f32_16x16x32_bf16 v[64:67], v[136:139], v[168:171], v[64:67]
	v_mfma_f32_16x16x32_bf16 v[56:59], v[144:147], v[168:171], v[56:59]
	v_mfma_f32_16x16x32_bf16 v[48:51], v[136:139], v[176:179], v[48:51]
	v_mfma_f32_16x16x32_bf16 v[40:43], v[144:147], v[176:179], v[40:43]
	v_mfma_f32_16x16x32_bf16 v[32:35], v[136:139], v[184:187], v[32:35]
	v_mfma_f32_16x16x32_bf16 v[24:27], v[144:147], v[184:187], v[24:27]
	v_mfma_f32_16x16x32_bf16 v[16:19], v[136:139], v[192:195], v[16:19]
	v_mfma_f32_16x16x32_bf16 v[8:11], v[144:147], v[192:195], v[8:11]
	s_setprio 0
	s_setprio 1
	v_mfma_f32_16x16x32_bf16 v[60:63], v[148:151], v[164:167], v[60:63]
	v_mfma_f32_16x16x32_bf16 v[52:55], v[156:159], v[164:167], v[52:55]
	v_mfma_f32_16x16x32_bf16 v[44:47], v[148:151], v[172:175], v[44:47]
	v_mfma_f32_16x16x32_bf16 v[36:39], v[156:159], v[172:175], v[36:39]
	v_mfma_f32_16x16x32_bf16 v[28:31], v[148:151], v[180:183], v[28:31]
	v_mfma_f32_16x16x32_bf16 v[20:23], v[156:159], v[180:183], v[20:23]
	v_mfma_f32_16x16x32_bf16 v[12:15], v[148:151], v[188:191], v[12:15]
	v_mfma_f32_16x16x32_bf16 v[4:7], v[156:159], v[188:191], v[4:7]
	v_mfma_f32_16x16x32_bf16 v[60:63], v[152:155], v[168:171], v[60:63]
	v_mfma_f32_16x16x32_bf16 v[52:55], v[160:163], v[168:171], v[52:55]
	v_mfma_f32_16x16x32_bf16 v[44:47], v[152:155], v[176:179], v[44:47]
	v_mfma_f32_16x16x32_bf16 v[36:39], v[160:163], v[176:179], v[36:39]
	v_mfma_f32_16x16x32_bf16 v[28:31], v[152:155], v[184:187], v[28:31]
	v_mfma_f32_16x16x32_bf16 v[20:23], v[160:163], v[184:187], v[20:23]
	v_mfma_f32_16x16x32_bf16 v[12:15], v[152:155], v[192:195], v[12:15]
	v_mfma_f32_16x16x32_bf16 v[4:7], v[160:163], v[192:195], v[4:7]
	s_setprio 0
	s_barrier
	s_add_u32 s0, s0, 0x100
	s_addc_u32 s1, s1, 0
	s_add_u32 s3, s3, 0x100
	s_addc_u32 s16, s16, 0
	s_cmp_ge_u32 s17, s61
	s_mov_b32 s14, s17
	s_cbranch_scc0 .LBB0_407
	s_branch .Lpeel1_exit

; #define PG8_BAR __builtin_amdgcn_s_barrier()
; __device__ __forceinline__ void gemm_phase(LAS unsigned char* lds, const Gemm g, const StaticOrder& S, const LAS Epi* Ep, const int tid) {
;     ...
;         if (!has_next) break;
; #pragma unroll
;         for (int a = 0; a < 2; ++a)
; #pragma unroll
;             for (int b = 0; b < 2; ++b)
; #pragma unroll
;                 for (int m = 0; m < 4; ++m)
; #pragma unroll
;                     for (int n = 0; n < 2; ++n) acc[a][b][m][n] = (f32x4){0.f, 0.f, 0.f, 0.f};
;         cur = nxt; cA = nA; cB = nB; ++ui;
;         if (wr == 1) PG8_BAR;
.LBB0_642:
	s_and_b64 vcc, exec, s[46:47]
	s_mov_b64 s[0:1], -1
	s_cbranch_vccnz .LBB0_399
	s_mov_b32 s32, 0
	s_andn2_b64 vcc, exec, s[6:7]
	s_cbranch_vccnz .LBB0_398
	s_mov_b32 s32, 1
	s_branch .LBB0_398

; __device__ __forceinline__ unsigned xb_ld(unsigned* p)              { return __hip_atomic_load(p, __ATOMIC_RELAXED, __HIP_MEMORY_SCOPE_AGENT); }
; __device__ __forceinline__ unsigned xb_add(unsigned* p, unsigned v) { return __hip_atomic_fetch_add(p, v, __ATOMIC_RELAXED, __HIP_MEMORY_SCOPE_AGENT); }
; #define XB_SPIN(cond, bar) do { unsigned _sp = 0; while (cond) { __builtin_amdgcn_s_sleep(6); \
;     if ((++_sp & 255u) == 0u) { if (xb_ld(&(bar)[XB_TMO])) break; if (_sp > XB_SPIN_CAP) { atomicAdd(&(bar)[XB_TMO], 1u); break; } } } } while (0)
; __device__ __forceinline__ void xcd_barrier(const XcdBarrier& b) {
;     ...
;         const unsigned old = xb_add(&bar[XB_XSUB(b.x)], 1u);
;         const unsigned gen = old / nloc;
;         if (old + 1u == (gen + 1u) * nloc) {
;             __builtin_amdgcn_fence(__ATOMIC_RELEASE, "agent");
;             asm volatile("s_waitcnt vmcnt(0)" ::: "memory");
;             const unsigned og = xb_add(&bar[XB_TOP], 1u);
;             const unsigned tg = og / nx;
;             if (og + 1u == (tg + 1u) * nx) xb_add(&bar[XB_TOPGEN], 1u);
;             else XB_SPIN(xb_ld(&bar[XB_TOPGEN]) == tg, bar);
;             __builtin_amdgcn_fence(__ATOMIC_ACQUIRE, "agent");
;             xb_add(&bar[XB_XGEN(b.x)], 1u);
;             asm volatile("s_waitcnt vmcnt(0)" ::: "memory");
;         } else {
;             XB_SPIN(xb_ld(&bar[XB_XGEN(b.x)]) == gen, bar);
.LBB0_701:
	s_or_b64 exec, exec, s[6:7]
	v_cvt_f32_u32_e32 v5, v2
	s_waitcnt vmcnt(0)
	v_readfirstlane_b32 s3, v4
	v_sub_u32_e32 v4, 0, v2
	v_rcp_iflag_f32_e32 v5, v5
	v_add_u32_e32 v6, s3, v1
	v_mul_f32_e32 v5, 0x4f7ffffe, v5
	v_cvt_u32_f32_e32 v5, v5
	v_mul_lo_u32 v1, v4, v5
	v_mul_hi_u32 v1, v5, v1
	v_add_u32_e32 v1, v5, v1
	v_mul_hi_u32 v1, v6, v1
	v_mul_lo_u32 v4, v1, v2
	v_sub_u32_e32 v4, v6, v4
	v_add_u32_e32 v5, 1, v1
	v_cmp_ge_u32_e32 vcc, v4, v2
	s_nop 1
	v_cndmask_b32_e32 v1, v1, v5, vcc
	v_sub_u32_e32 v5, v4, v2
	v_cndmask_b32_e32 v4, v4, v5, vcc
	v_add_u32_e32 v5, 1, v1
	v_cmp_ge_u32_e32 vcc, v4, v2
	v_add_u32_e32 v4, 1, v6
	s_nop 0
	v_cndmask_b32_e32 v1, v1, v5, vcc
	v_mul_lo_u32 v5, v2, v1
	v_add_u32_e32 v2, v5, v2
	v_cmp_ne_u32_e32 vcc, v4, v2
	s_and_saveexec_b64 s[6:7], vcc
	s_xor_b64 s[6:7], exec, s[6:7]
	s_cbranch_execz .LBB0_715
	v_readlane_b32 s8, v253, 62
	v_readlane_b32 s9, v253, 63
	s_waitcnt lgkmcnt(0)
	s_nop 3
	global_load_dword v0, v3, s[8:9] sc1
	s_waitcnt vmcnt(0)
	v_cmp_eq_u32_e32 vcc, v0, v1
	s_and_saveexec_b64 s[8:9], vcc
	s_cbranch_execz .LBB0_714
	s_mov_b32 s3, 1
	s_mov_b64 s[10:11], 0
	s_branch .LBB0_705

; __device__ __forceinline__ unsigned xb_ld(unsigned* p)              { return __hip_atomic_load(p, __ATOMIC_RELAXED, __HIP_MEMORY_SCOPE_AGENT); }
; #define XB_SPIN(cond, bar) do { unsigned _sp = 0; while (cond) { __builtin_amdgcn_s_sleep(6); \
;     if ((++_sp & 255u) == 0u) { if (xb_ld(&(bar)[XB_TMO])) break; if (_sp > XB_SPIN_CAP) { atomicAdd(&(bar)[XB_TMO], 1u); break; } } } } while (0)
; __device__ __forceinline__ void xcd_barrier(const XcdBarrier& b) {
;     ...
;             XB_SPIN(xb_ld(&bar[XB_XGEN(b.x)]) == gen, bar);
;             __builtin_amdgcn_fence(__ATOMIC_ACQUIRE, "agent");
.LBB0_707:
	v_readlane_b32 s14, v253, 62
	v_readlane_b32 s15, v253, 63
	s_add_i32 s3, s3, 1
	s_mov_b64 s[16:17], -1
	s_nop 2
	global_load_dword v0, v3, s[14:15] sc1
	s_waitcnt vmcnt(0)
	v_cmp_ne_u32_e32 vcc, v0, v1
	s_orn2_b64 s[14:15], vcc, exec
	s_branch .LBB0_704

; __device__ __forceinline__ unsigned xb_add(unsigned* p, unsigned v) { return __hip_atomic_fetch_add(p, v, __ATOMIC_RELAXED, __HIP_MEMORY_SCOPE_AGENT); }
; __device__ __forceinline__ void xcd_barrier(const XcdBarrier& b) {
;     ...
;             __builtin_amdgcn_fence(__ATOMIC_ACQUIRE, "agent");
;             xb_add(&bar[XB_XGEN(b.x)], 1u);
.LBB0_732:
	s_or_b64 exec, exec, s[6:7]
	s_mov_b64 s[6:7], exec
	v_mbcnt_lo_u32_b32 v0, s6, 0
	v_mbcnt_hi_u32_b32 v0, s7, v0
	v_cmp_eq_u32_e32 vcc, 0, v0
	s_waitcnt vmcnt(0)
	buffer_inv sc1
	s_and_saveexec_b64 s[8:9], vcc
	s_cbranch_execz .LBB0_734
	s_bcnt1_i32_b64 s3, s[6:7]
	v_readlane_b32 s6, v253, 58
	v_mov_b32_e32 v0, s3
	v_readlane_b32 s7, v253, 59
	s_nop 4
.LBB0_734:
	s_or_b64 exec, exec, s[8:9]
	s_waitcnt vmcnt(0)

; __device__ __forceinline__ unsigned xb_ld(unsigned* p)              { return __hip_atomic_load(p, __ATOMIC_RELAXED, __HIP_MEMORY_SCOPE_AGENT); }
; __device__ __forceinline__ unsigned xb_add(unsigned* p, unsigned v) { return __hip_atomic_fetch_add(p, v, __ATOMIC_RELAXED, __HIP_MEMORY_SCOPE_AGENT); }
; #define XB_SPIN(cond, bar) do { unsigned _sp = 0; while (cond) { __builtin_amdgcn_s_sleep(6); \
;     if ((++_sp & 255u) == 0u) { if (xb_ld(&(bar)[XB_TMO])) break; if (_sp > XB_SPIN_CAP) { atomicAdd(&(bar)[XB_TMO], 1u); break; } } } } while (0)
; __device__ __forceinline__ void xcd_barrier(const XcdBarrier& b) {
;     ...
;         const unsigned old = xb_add(&bar[XB_XSUB(b.x)], 1u);
;         const unsigned gen = old / nloc;
;         if (old + 1u == (gen + 1u) * nloc) {
;             __builtin_amdgcn_fence(__ATOMIC_RELEASE, "agent");
;             asm volatile("s_waitcnt vmcnt(0)" ::: "memory");
;             const unsigned og = xb_add(&bar[XB_TOP], 1u);
;             const unsigned tg = og / nx;
;             if (og + 1u == (tg + 1u) * nx) xb_add(&bar[XB_TOPGEN], 1u);
;             else XB_SPIN(xb_ld(&bar[XB_TOPGEN]) == tg, bar);
;             __builtin_amdgcn_fence(__ATOMIC_ACQUIRE, "agent");
;             xb_add(&bar[XB_XGEN(b.x)], 1u);
;             asm volatile("s_waitcnt vmcnt(0)" ::: "memory");
;         } else {
;             XB_SPIN(xb_ld(&bar[XB_XGEN(b.x)]) == gen, bar);
.LBB0_1069:
	s_or_b64 exec, exec, s[10:11]
	v_cvt_f32_u32_e32 v4, v2
	s_waitcnt vmcnt(0)
	v_readfirstlane_b32 s2, v3
	v_sub_u32_e32 v3, 0, v2
	v_rcp_iflag_f32_e32 v4, v4
	v_add_u32_e32 v5, s2, v1
	v_mul_f32_e32 v4, 0x4f7ffffe, v4
	v_cvt_u32_f32_e32 v4, v4
	v_mul_lo_u32 v1, v3, v4
	v_mul_hi_u32 v1, v4, v1
	v_add_u32_e32 v1, v4, v1
	v_mul_hi_u32 v1, v5, v1
	v_mul_lo_u32 v3, v1, v2
	v_sub_u32_e32 v3, v5, v3
	v_add_u32_e32 v4, 1, v1
	v_cmp_ge_u32_e32 vcc, v3, v2
	s_nop 1
	v_cndmask_b32_e32 v1, v1, v4, vcc
	v_sub_u32_e32 v4, v3, v2
	v_cndmask_b32_e32 v3, v3, v4, vcc
	v_add_u32_e32 v4, 1, v1
	v_cmp_ge_u32_e32 vcc, v3, v2
	v_add_u32_e32 v3, 1, v5
	s_nop 0
	v_cndmask_b32_e32 v1, v1, v4, vcc
	v_mul_lo_u32 v4, v2, v1
	v_add_u32_e32 v2, v4, v2
	v_cmp_ne_u32_e32 vcc, v3, v2
	s_and_saveexec_b64 s[2:3], vcc
	s_xor_b64 s[8:9], exec, s[2:3]
	s_cbranch_execz .LBB0_1083
	s_waitcnt lgkmcnt(0)
	v_readlane_b32 s12, v253, 6
	v_readlane_b32 s13, v253, 7
	v_mov_b32_e32 v0, 0
	s_add_u32 s12, s12, 0x3500
	s_addc_u32 s13, s13, 0
	global_load_dword v0, v0, s[12:13] sc1
	s_waitcnt vmcnt(0)
	v_cmp_eq_u32_e32 vcc, v0, v1
	s_and_saveexec_b64 s[10:11], vcc
	s_cbranch_execz .LBB0_1082
	s_mov_b32 s2, 1
	s_mov_b64 s[14:15], 0
	v_mov_b32_e32 v0, 0
	s_branch .LBB0_1073

; __device__ __forceinline__ unsigned xb_add(unsigned* p, unsigned v) { return __hip_atomic_fetch_add(p, v, __ATOMIC_RELAXED, __HIP_MEMORY_SCOPE_AGENT); }
; __device__ __forceinline__ void xcd_barrier(const XcdBarrier& b) {
;     ...
;             __builtin_amdgcn_fence(__ATOMIC_ACQUIRE, "agent");
;             xb_add(&bar[XB_XGEN(b.x)], 1u);
.LBB0_1100:
	s_or_b64 exec, exec, s[8:9]
	s_mov_b64 s[8:9], exec
	v_mbcnt_lo_u32_b32 v0, s8, 0
	v_mbcnt_hi_u32_b32 v0, s9, v0
	v_cmp_eq_u32_e32 vcc, 0, v0
	s_waitcnt vmcnt(0)
	buffer_inv sc1
	s_and_saveexec_b64 s[10:11], vcc
	s_cbranch_execz .LBB0_1102
	s_bcnt1_i32_b64 s2, s[8:9]
	v_mov_b32_e32 v0, 0x2000
	v_mov_b32_e32 v1, s2
.LBB0_1102:
	s_or_b64 exec, exec, s[10:11]
	s_waitcnt vmcnt(0)

; __device__ __forceinline__ unsigned xb_add(unsigned* p, unsigned v) { return __hip_atomic_fetch_add(p, v, __ATOMIC_RELAXED, __HIP_MEMORY_SCOPE_AGENT); }
; __device__ __forceinline__ void xcd_barrier(const XcdBarrier& b) {
;     ...
;             __builtin_amdgcn_fence(__ATOMIC_ACQUIRE, "agent");
;             xb_add(&bar[XB_XGEN(b.x)], 1u);
.LBB0_1310:
	s_or_b64 exec, exec, s[8:9]
	s_mov_b64 s[8:9], exec
	v_mbcnt_lo_u32_b32 v0, s8, 0
	v_mbcnt_hi_u32_b32 v0, s9, v0
	v_cmp_eq_u32_e32 vcc, 0, v0
	s_waitcnt vmcnt(0)
	buffer_inv sc1
	s_and_saveexec_b64 s[10:11], vcc
	s_cbranch_execz .LBB0_1312
	s_bcnt1_i32_b64 s2, s[8:9]
	v_mov_b32_e32 v0, 0x2000
	v_mov_b32_e32 v1, s2
.LBB0_1312:
	s_or_b64 exec, exec, s[10:11]
	s_waitcnt vmcnt(0)

; __device__ __forceinline__ unsigned xb_ld(unsigned* p)              { return __hip_atomic_load(p, __ATOMIC_RELAXED, __HIP_MEMORY_SCOPE_AGENT); }
; __device__ __forceinline__ unsigned xb_add(unsigned* p, unsigned v) { return __hip_atomic_fetch_add(p, v, __ATOMIC_RELAXED, __HIP_MEMORY_SCOPE_AGENT); }
; #define XB_SPIN(cond, bar) do { unsigned _sp = 0; while (cond) { __builtin_amdgcn_s_sleep(6); \
;     if ((++_sp & 255u) == 0u) { if (xb_ld(&(bar)[XB_TMO])) break; if (_sp > XB_SPIN_CAP) { atomicAdd(&(bar)[XB_TMO], 1u); break; } } } } while (0)
; __device__ __forceinline__ void xcd_barrier(const XcdBarrier& b) {
;     ...
;         const unsigned old = xb_add(&bar[XB_XSUB(b.x)], 1u);
;         const unsigned gen = old / nloc;
;         if (old + 1u == (gen + 1u) * nloc) {
;             __builtin_amdgcn_fence(__ATOMIC_RELEASE, "agent");
;             asm volatile("s_waitcnt vmcnt(0)" ::: "memory");
;             const unsigned og = xb_add(&bar[XB_TOP], 1u);
;             const unsigned tg = og / nx;
;             if (og + 1u == (tg + 1u) * nx) xb_add(&bar[XB_TOPGEN], 1u);
;             else XB_SPIN(xb_ld(&bar[XB_TOPGEN]) == tg, bar);
;             __builtin_amdgcn_fence(__ATOMIC_ACQUIRE, "agent");
;             xb_add(&bar[XB_XGEN(b.x)], 1u);
;             asm volatile("s_waitcnt vmcnt(0)" ::: "memory");
;         } else {
;             XB_SPIN(xb_ld(&bar[XB_XGEN(b.x)]) == gen, bar);
.LBB0_1352:
	s_or_b64 exec, exec, s[8:9]
	v_cvt_f32_u32_e32 v4, v2
	s_waitcnt vmcnt(0)
	v_readfirstlane_b32 s2, v3
	v_sub_u32_e32 v3, 0, v2
	v_rcp_iflag_f32_e32 v4, v4
	v_add_u32_e32 v5, s2, v1
	v_mul_f32_e32 v4, 0x4f7ffffe, v4
	v_cvt_u32_f32_e32 v4, v4
	v_mul_lo_u32 v1, v3, v4
	v_mul_hi_u32 v1, v4, v1
	v_add_u32_e32 v1, v4, v1
	v_mul_hi_u32 v1, v5, v1
	v_mul_lo_u32 v3, v1, v2
	v_sub_u32_e32 v3, v5, v3
	v_add_u32_e32 v4, 1, v1
	v_cmp_ge_u32_e32 vcc, v3, v2
	s_nop 1
	v_cndmask_b32_e32 v1, v1, v4, vcc
	v_sub_u32_e32 v4, v3, v2
	v_cndmask_b32_e32 v3, v3, v4, vcc
	v_add_u32_e32 v4, 1, v1
	v_cmp_ge_u32_e32 vcc, v3, v2
	v_add_u32_e32 v3, 1, v5
	s_nop 0
	v_cndmask_b32_e32 v1, v1, v4, vcc
	v_mul_lo_u32 v4, v2, v1
	v_add_u32_e32 v2, v4, v2
	v_cmp_ne_u32_e32 vcc, v3, v2
	s_and_saveexec_b64 s[2:3], vcc
	s_xor_b64 s[6:7], exec, s[2:3]
	s_cbranch_execz .LBB0_1366
	s_waitcnt lgkmcnt(0)
	v_readlane_b32 s10, v253, 6
	v_readlane_b32 s11, v253, 7
	v_mov_b32_e32 v0, 0
	s_add_u32 s10, s10, 0x3500
	s_addc_u32 s11, s11, 0
	global_load_dword v0, v0, s[10:11] sc1
	s_waitcnt vmcnt(0)
	v_cmp_eq_u32_e32 vcc, v0, v1
	s_and_saveexec_b64 s[8:9], vcc
	s_cbranch_execz .LBB0_1365
	s_mov_b32 s2, 1
	s_mov_b64 s[12:13], 0
	v_mov_b32_e32 v0, 0
	s_branch .LBB0_1356

; __device__ __forceinline__ unsigned xb_add(unsigned* p, unsigned v) { return __hip_atomic_fetch_add(p, v, __ATOMIC_RELAXED, __HIP_MEMORY_SCOPE_AGENT); }
; __device__ __forceinline__ void xcd_barrier(const XcdBarrier& b) {
;     ...
;             __builtin_amdgcn_fence(__ATOMIC_ACQUIRE, "agent");
;             xb_add(&bar[XB_XGEN(b.x)], 1u);
.LBB0_1383:
	s_or_b64 exec, exec, s[6:7]
	s_mov_b64 s[6:7], exec
	v_mbcnt_lo_u32_b32 v0, s6, 0
	v_mbcnt_hi_u32_b32 v0, s7, v0
	v_cmp_eq_u32_e32 vcc, 0, v0
	s_waitcnt vmcnt(0)
	buffer_inv sc1
	s_and_saveexec_b64 s[8:9], vcc
	s_cbranch_execz .LBB0_1385
	s_bcnt1_i32_b64 s2, s[6:7]
	v_mov_b32_e32 v0, 0x2000
	v_mov_b32_e32 v1, s2
.LBB0_1385:
	s_or_b64 exec, exec, s[8:9]
	s_waitcnt vmcnt(0)

; #define PG8_STAGE(bufoff, gbase, voff) do { _Pragma("unroll") for (int _i = 0; _i < 2; ++_i) \
;         __builtin_amdgcn_global_load_lds((const unsigned*)((const char*)(gbase) + (voff)[_i]), (LAS unsigned*)(lds + (bufoff) + ldsw + _i * 8192), 16, 0, 0); } while (0)
; #define PG8_WAIT_V(n) asm volatile("s_waitcnt vmcnt(" #n ")" ::: "memory")
; #define PG8_BAR __builtin_amdgcn_s_barrier()
; __device__ __forceinline__ void gemm_phase(LAS unsigned char* lds, const Gemm g, const StaticOrder& S, const LAS Epi* Ep, const int tid) {
;     ...
;     PG8_STAGE(PG8_SB(0, 0), cB, voffB); PG8_STAGE(PG8_SB(0, 1), cB + hstepB, voffB); PG8_STAGE(PG8_SA(0, 0), cA, voffA); PG8_STAGE(PG8_SA(0, 1), cA + hstepA, voffA);
;     if (wr == 1) PG8_BAR;
;     PG8_WAIT_V(2); PG8_BAR;
;     PG8_STAGE(PG8_SB(1, 0), cB + kstep, voffB); PG8_STAGE(PG8_SA(1, 0), cA + kstep, voffA); PG8_STAGE(PG8_SB(1, 1), cB + hstepB + kstep, voffB);
;     PG8_WAIT_V(6); PG8_BAR;
.LBB0_1424:
	s_add_i32 m0, s67, 0x18000
	v_lshl_add_u64 v[2:3], v[2:3], 0, s[88:89]
	s_lshr_b32 s16, s4, 6
	s_lshl_b32 s21, s10, 6
	s_lshl_b32 s4, s10, 13
	s_waitcnt vmcnt(2)
	s_barrier
	global_load_lds_dwordx4 v[2:3], off
	v_lshl_add_u64 v[2:3], v[4:5], 0, s[88:89]
	s_add_i32 m0, s67, 0x1a000
	s_add_i32 s10, s67, 0x8000
	global_load_lds_dwordx4 v[2:3], off
	v_lshl_add_u64 v[2:3], v[10:11], 0, s[88:89]
	s_mov_b32 m0, s10
	s_add_i32 s11, s67, 0xa000
	global_load_lds_dwordx4 v[2:3], off
	v_lshl_add_u64 v[2:3], v[12:13], 0, s[88:89]
	s_mov_b32 m0, s11
	v_lshlrev_b32_e32 v14, 2, v237
	global_load_lds_dwordx4 v[2:3], off
	s_add_i32 m0, s67, 0x1c000
	v_lshl_add_u64 v[2:3], v[6:7], 0, s[88:89]
	global_load_lds_dwordx4 v[2:3], off
	v_lshl_add_u64 v[2:3], v[8:9], 0, s[88:89]
	s_add_i32 m0, s67, 0x1e000
	v_lshl_or_b32 v0, v237, 6, v245
	global_load_lds_dwordx4 v[2:3], off
	v_and_b32_e32 v14, 32, v14
	v_bitop3_b32 v0, v0, s4, v14 bitop3:0xde
	s_lshl_b32 s4, s9, 5
	s_and_b32 s4, s4, 0x60
	s_add_i32 s20, s16, -2
	s_cmpk_lt_u32 s8, 0x100
	s_cselect_b64 s[30:31], -1, 0
	s_and_b32 s5, s8, 0x7ffffc0
	s_lshl_b32 s12, s3, 2
	v_or_b32_e32 v2, s5, v236
	s_abs_i32 s8, s12
	v_lshlrev_b32_e32 v248, 5, v2
	v_cvt_f32_u32_e32 v2, s8
	v_lshl_or_b32 v247, s4, 7, v246
	v_or_b32_e32 v204, s4, v244
	s_bfe_i32 s13, s3, 0x1001d
	v_rcp_iflag_f32_e32 v2, v2
	s_sub_i32 s3, 0, s8
	s_waitcnt vmcnt(6)
	s_ashr_i32 s17, s59, 31
	v_mul_f32_e32 v2, 0x4f7ffffe, v2
	v_cvt_u32_f32_e32 v2, v2
	s_mov_b32 s25, s87
	s_lshr_b32 s61, s24, 3
	s_mov_b32 s9, 0
	v_readfirstlane_b32 s4, v2
	s_mul_i32 s3, s3, s4
	s_mul_hi_u32 s3, s4, s3
	s_add_i32 s40, s4, s3
	v_lshl_add_u64 v[206:207], s[86:87], 0, v[196:197]
	v_lshl_add_u64 v[208:209], s[86:87], 0, v[200:201]
	s_mov_b32 s41, -1
	v_add_u32_e32 v249, 0, v0
	s_barrier
	s_mov_b32 s32, 0
	s_branch .LBB0_1427

; #define PG8_STAGE(bufoff, gbase, voff) do { _Pragma("unroll") for (int _i = 0; _i < 2; ++_i) \
;         __builtin_amdgcn_global_load_lds((const unsigned*)((const char*)(gbase) + (voff)[_i]), (LAS unsigned*)(lds + (bufoff) + ldsw + _i * 8192), 16, 0, 0); } while (0)
; #define PG8_LDA(dst, b, h) do { _Pragma("unroll") for (int m = 0; m < 4; ++m) _Pragma("unroll") for (int k = 0; k < 2; ++k) dst[m][k] = *(const LAS bf16x8*)(lds + PG8_SA(b, h) + aoff + m * 2048 + k * 1024); } while (0)
; #define PG8_LDB(dst, b, h) do { _Pragma("unroll") for (int n = 0; n < 2; ++n) _Pragma("unroll") for (int k = 0; k < 2; ++k) dst[n][k] = *(const LAS bf16x8*)(lds + PG8_SB(b, h) + boff + n * 2048 + k * 1024); } while (0)
; #define PG8_MMA(ai, bj, At, Bt) do { __builtin_amdgcn_s_setprio(1); _Pragma("unroll") for (int m = 0; m < 4; ++m) _Pragma("unroll") for (int n = 0; n < 2; ++n) _Pragma("unroll") for (int k = 0; k < 2; ++k) \
;         acc[ai][bj][m][n] = __builtin_amdgcn_mfma_f32_16x16x32_bf16(Bt[n][k], At[m][k], acc[ai][bj][m][n], 0, 0, 0); __builtin_amdgcn_s_setprio(0); } while (0)
; #define PG8_WAIT_V(n) asm volatile("s_waitcnt vmcnt(" #n ")" ::: "memory")
; #define PG8_WAIT_L(n) asm volatile("s_waitcnt lgkmcnt(" #n ")" ::: "memory")
; __device__ __forceinline__ void gemm_phase(LAS unsigned char* lds, const Gemm g, const StaticOrder& S, const LAS Epi* Ep, const int tid) {
;     ...
;         const bool has_next = S.next(ui + 1, nxt);
;         const char* nA = has_next ? (const char*)g.A + (size_t)nxt.pm * tstepA : cA; const char* nB = has_next ? (const char*)g.Bt + (size_t)nxt.pn * tstepB : cB;
;         for (int t = 0; t < nt; t += 2) {
;             const bool last = (t == nt - 2);
;             const char* a1 = cA + (size_t)(t + 1) * kstep;
;             const char* a2 = last ? nA : cA + (size_t)(t + 2) * kstep; const char* b2 = last ? nB : cB + (size_t)(t + 2) * kstep;
;             const char* a3 = a2 + kstep; const char* b3 = b2 + kstep;
;             PG8_LDB(B0, 0, 0); PG8_LDB(B1, 0, 1); PG8_SCHED; PG8_LDA(At, 0, 0); PG8_STAGE(PG8_SA(1, 1), a1 + hstepA, voffA);
;             PG8_WAIT_V(8); PG8_WAIT_L(0); PG8_BAR; PG8_MMA(0, 0, At, B0); PG8_MMA(0, 1, At, B1); PG8_BAR; PG8_SCHED;
;             PG8_LDA(At, 0, 1); PG8_STAGE(PG8_SB(0, 0), b2, voffB); PG8_STAGE(PG8_SB(0, 1), b2 + hstepB, voffB); PG8_STAGE(PG8_SA(0, 0), a2, voffA);
;     ...
;         if (wr == 1) PG8_BAR;
.LBB0_1433:
	s_add_u32 s0, s0, 0x80
	s_addc_u32 s1, s1, 0
	s_add_u32 s3, s38, 0x100
	s_addc_u32 s5, s39, 0
	s_mov_b32 s23, 0
	s_cmp_eq_u32 s32, 0
	s_cbranch_scc1 .Lstag2_skip
	s_barrier
.Lstag2_skip:
	s_add_i32 s48, s23, 2
	s_add_u32 s38, s0, 0x80
	s_addc_u32 s39, s1, 0
	s_add_i32 s49, 0, 0x10000
	s_cmp_eq_u32 s20, s23
	s_cselect_b32 s39, s35, s39
	s_cselect_b32 s38, s34, s38
	v_add_u32_e32 v0, s49, v247
	s_cselect_b32 s51, s37, s5
	s_cselect_b32 s50, s36, s3
	s_add_i32 s23, 0, 0x14000
	s_waitcnt lgkmcnt(0)
	ds_read_b128 v[130:133], v0
	ds_read_b128 v[134:137], v0 offset:1024
	ds_read_b128 v[138:141], v0 offset:2048
	ds_read_b128 v[142:145], v0 offset:3072
	v_add_u32_e32 v0, s23, v247
	ds_read_b128 v[146:149], v0
	ds_read_b128 v[150:153], v0 offset:1024
	ds_read_b128 v[154:157], v0 offset:2048
	ds_read_b128 v[158:161], v0 offset:3072
	v_lshl_add_u64 v[210:211], s[0:1], 0, v[206:207]
	s_add_i32 m0, s67, 0xc000
	ds_read_b128 v[162:165], v249
	ds_read_b128 v[166:169], v249 offset:1024
	ds_read_b128 v[170:173], v249 offset:2048
	ds_read_b128 v[174:177], v249 offset:3072
	ds_read_b128 v[178:181], v249 offset:4096
	ds_read_b128 v[182:185], v249 offset:5120
	ds_read_b128 v[186:189], v249 offset:6144
	ds_read_b128 v[190:193], v249 offset:7168
	global_load_lds_dwordx4 v[210:211], off
	v_lshl_add_u64 v[210:211], s[0:1], 0, v[208:209]
	s_add_i32 m0, s67, 0xe000
	s_nop 0
	global_load_lds_dwordx4 v[210:211], off
	s_waitcnt vmcnt(8)
	s_waitcnt lgkmcnt(0)
	s_barrier
	s_setprio 1
	s_waitcnt lgkmcnt(0)
	v_mfma_f32_16x16x32_bf16 v[126:129], v[130:133], v[162:165], 0
	v_mfma_f32_16x16x32_bf16 v[118:121], v[138:141], v[162:165], 0
	v_mfma_f32_16x16x32_bf16 v[110:113], v[130:133], v[170:173], 0
	v_mfma_f32_16x16x32_bf16 v[102:105], v[138:141], v[170:173], 0
	v_mfma_f32_16x16x32_bf16 v[94:97], v[130:133], v[178:181], 0
	v_mfma_f32_16x16x32_bf16 v[86:89], v[138:141], v[178:181], 0
	v_mfma_f32_16x16x32_bf16 v[78:81], v[130:133], v[186:189], 0
	v_mfma_f32_16x16x32_bf16 v[70:73], v[138:141], v[186:189], 0
	v_mfma_f32_16x16x32_bf16 v[126:129], v[134:137], v[166:169], v[126:129]
	v_mfma_f32_16x16x32_bf16 v[118:121], v[142:145], v[166:169], v[118:121]
	v_mfma_f32_16x16x32_bf16 v[110:113], v[134:137], v[174:177], v[110:113]
	v_mfma_f32_16x16x32_bf16 v[102:105], v[142:145], v[174:177], v[102:105]
	v_mfma_f32_16x16x32_bf16 v[94:97], v[134:137], v[182:185], v[94:97]
	v_mfma_f32_16x16x32_bf16 v[86:89], v[142:145], v[182:185], v[86:89]
	v_mfma_f32_16x16x32_bf16 v[78:81], v[134:137], v[190:193], v[78:81]
	v_mfma_f32_16x16x32_bf16 v[70:73], v[142:145], v[190:193], v[70:73]
	s_setprio 0
	s_setprio 1
	v_mfma_f32_16x16x32_bf16 v[122:125], v[146:149], v[162:165], 0
	v_mfma_f32_16x16x32_bf16 v[114:117], v[154:157], v[162:165], 0
	v_mfma_f32_16x16x32_bf16 v[106:109], v[146:149], v[170:173], 0
	v_mfma_f32_16x16x32_bf16 v[98:101], v[154:157], v[170:173], 0
	v_mfma_f32_16x16x32_bf16 v[90:93], v[146:149], v[178:181], 0
	v_mfma_f32_16x16x32_bf16 v[82:85], v[154:157], v[178:181], 0
	v_mfma_f32_16x16x32_bf16 v[74:77], v[146:149], v[186:189], 0
	v_mfma_f32_16x16x32_bf16 v[66:69], v[154:157], v[186:189], 0
	v_mfma_f32_16x16x32_bf16 v[122:125], v[150:153], v[166:169], v[122:125]
	v_mfma_f32_16x16x32_bf16 v[114:117], v[158:161], v[166:169], v[114:117]
	v_mfma_f32_16x16x32_bf16 v[106:109], v[150:153], v[174:177], v[106:109]
	v_mfma_f32_16x16x32_bf16 v[98:101], v[158:161], v[174:177], v[98:101]
	v_mfma_f32_16x16x32_bf16 v[90:93], v[150:153], v[182:185], v[90:93]
	v_mfma_f32_16x16x32_bf16 v[82:85], v[158:161], v[182:185], v[82:85]
	v_mfma_f32_16x16x32_bf16 v[74:77], v[150:153], v[190:193], v[74:77]
	v_mfma_f32_16x16x32_bf16 v[66:69], v[158:161], v[190:193], v[66:69]
	s_setprio 0
	s_barrier
	s_add_i32 s49, s49, s2
	v_lshl_add_u64 v[210:211], s[50:51], 0, v[198:199]
	s_mov_b32 m0, s49
	ds_read_b128 v[162:165], v249 offset:16384
	ds_read_b128 v[166:169], v249 offset:17408
	ds_read_b128 v[170:173], v249 offset:18432
	ds_read_b128 v[174:177], v249 offset:19456
	ds_read_b128 v[178:181], v249 offset:20480
	ds_read_b128 v[182:185], v249 offset:21504
	ds_read_b128 v[186:189], v249 offset:22528
	ds_read_b128 v[190:193], v249 offset:23552
	global_load_lds_dwordx4 v[210:211], off
	s_add_i32 m0, s49, 0x2000
	v_lshl_add_u64 v[212:213], s[50:51], 0, v[202:203]
	s_add_u32 s50, s50, s74
	s_addc_u32 s51, s51, 0
	s_add_i32 s23, s23, s2
	global_load_lds_dwordx4 v[212:213], off
	v_lshl_add_u64 v[214:215], s[50:51], 0, v[198:199]
	s_mov_b32 m0, s23
	v_lshl_add_u64 v[216:217], s[50:51], 0, v[202:203]
	global_load_lds_dwordx4 v[214:215], off
	s_add_i32 m0, s23, 0x2000
	v_lshl_add_u64 v[218:219], s[38:39], 0, v[196:197]
	global_load_lds_dwordx4 v[216:217], off
	s_mov_b32 m0, s67
	v_lshl_add_u64 v[220:221], s[38:39], 0, v[200:201]
	global_load_lds_dwordx4 v[218:219], off
	s_mov_b32 m0, s7
	s_nop 0
	global_load_lds_dwordx4 v[220:221], off
	s_waitcnt vmcnt(8)
	s_waitcnt lgkmcnt(0)
	s_barrier
; #define PG8_STAGE(bufoff, gbase, voff) do { _Pragma("unroll") for (int _i = 0; _i < 2; ++_i) \
;         __builtin_amdgcn_global_load_lds((const unsigned*)((const char*)(gbase) + (voff)[_i]), (LAS unsigned*)(lds + (bufoff) + ldsw + _i * 8192), 16, 0, 0); } while (0)
; #define PG8_LDA(dst, b, h) do { _Pragma("unroll") for (int m = 0; m < 4; ++m) _Pragma("unroll") for (int k = 0; k < 2; ++k) dst[m][k] = *(const LAS bf16x8*)(lds + PG8_SA(b, h) + aoff + m * 2048 + k * 1024); } while (0)
; #define PG8_LDB(dst, b, h) do { _Pragma("unroll") for (int n = 0; n < 2; ++n) _Pragma("unroll") for (int k = 0; k < 2; ++k) dst[n][k] = *(const LAS bf16x8*)(lds + PG8_SB(b, h) + boff + n * 2048 + k * 1024); } while (0)
; #define PG8_MMA(ai, bj, At, Bt) do { __builtin_amdgcn_s_setprio(1); _Pragma("unroll") for (int m = 0; m < 4; ++m) _Pragma("unroll") for (int n = 0; n < 2; ++n) _Pragma("unroll") for (int k = 0; k < 2; ++k) \
;         acc[ai][bj][m][n] = __builtin_amdgcn_mfma_f32_16x16x32_bf16(Bt[n][k], At[m][k], acc[ai][bj][m][n], 0, 0, 0); __builtin_amdgcn_s_setprio(0); } while (0)
; #define PG8_WAIT_V(n) asm volatile("s_waitcnt vmcnt(" #n ")" ::: "memory")
; #define PG8_WAIT_L(n) asm volatile("s_waitcnt lgkmcnt(" #n ")" ::: "memory")
; #define PG8_BAR __builtin_amdgcn_s_barrier()
; #define PG8_SCHED __builtin_amdgcn_sched_barrier(0)
; __device__ __forceinline__ void gemm_phase(LAS unsigned char* lds, const Gemm g, const StaticOrder& S, const LAS Epi* Ep, const int tid) {
;     ...
;             PG8_WAIT_V(8); PG8_WAIT_L(0); PG8_BAR; PG8_MMA(1, 0, At, B0); PG8_MMA(1, 1, At, B1); PG8_BAR; PG8_SCHED;
;             PG8_LDB(B0, 1, 0); PG8_LDB(B1, 1, 1); PG8_SCHED; PG8_LDA(At, 1, 0); PG8_STAGE(PG8_SA(0, 1), a2 + hstepA, voffA);
;             PG8_WAIT_V(8); PG8_WAIT_L(0); PG8_BAR; PG8_MMA(0, 0, At, B0); PG8_MMA(0, 1, At, B1); PG8_BAR; PG8_SCHED;
	s_setprio 1
	s_waitcnt lgkmcnt(0)
	v_mfma_f32_16x16x32_bf16 v[62:65], v[130:133], v[162:165], 0
	v_mfma_f32_16x16x32_bf16 v[54:57], v[138:141], v[162:165], 0
	v_mfma_f32_16x16x32_bf16 v[46:49], v[130:133], v[170:173], 0
	v_mfma_f32_16x16x32_bf16 v[38:41], v[138:141], v[170:173], 0
	v_mfma_f32_16x16x32_bf16 v[30:33], v[130:133], v[178:181], 0
	v_mfma_f32_16x16x32_bf16 v[22:25], v[138:141], v[178:181], 0
	v_mfma_f32_16x16x32_bf16 v[14:17], v[130:133], v[186:189], 0
	v_mfma_f32_16x16x32_bf16 v[6:9], v[138:141], v[186:189], 0
	v_mfma_f32_16x16x32_bf16 v[62:65], v[134:137], v[166:169], v[62:65]
	v_mfma_f32_16x16x32_bf16 v[54:57], v[142:145], v[166:169], v[54:57]
	v_mfma_f32_16x16x32_bf16 v[46:49], v[134:137], v[174:177], v[46:49]
	v_mfma_f32_16x16x32_bf16 v[38:41], v[142:145], v[174:177], v[38:41]
	v_mfma_f32_16x16x32_bf16 v[30:33], v[134:137], v[182:185], v[30:33]
	v_mfma_f32_16x16x32_bf16 v[22:25], v[142:145], v[182:185], v[22:25]
	v_mfma_f32_16x16x32_bf16 v[14:17], v[134:137], v[190:193], v[14:17]
	v_mfma_f32_16x16x32_bf16 v[6:9], v[142:145], v[190:193], v[6:9]
	s_setprio 0
	s_setprio 1
	v_mfma_f32_16x16x32_bf16 v[58:61], v[146:149], v[162:165], 0
	v_mfma_f32_16x16x32_bf16 v[50:53], v[154:157], v[162:165], 0
	v_mfma_f32_16x16x32_bf16 v[42:45], v[146:149], v[170:173], 0
	v_mfma_f32_16x16x32_bf16 v[34:37], v[154:157], v[170:173], 0
	v_mfma_f32_16x16x32_bf16 v[26:29], v[146:149], v[178:181], 0
	v_mfma_f32_16x16x32_bf16 v[18:21], v[154:157], v[178:181], 0
	v_mfma_f32_16x16x32_bf16 v[10:13], v[146:149], v[186:189], 0
	v_mfma_f32_16x16x32_bf16 v[2:5], v[154:157], v[186:189], 0
	v_mfma_f32_16x16x32_bf16 v[58:61], v[150:153], v[166:169], v[58:61]
	v_mfma_f32_16x16x32_bf16 v[50:53], v[158:161], v[166:169], v[50:53]
	v_mfma_f32_16x16x32_bf16 v[42:45], v[150:153], v[174:177], v[42:45]
	v_mfma_f32_16x16x32_bf16 v[34:37], v[158:161], v[174:177], v[34:37]
	v_mfma_f32_16x16x32_bf16 v[26:29], v[150:153], v[182:185], v[26:29]
	v_mfma_f32_16x16x32_bf16 v[18:21], v[158:161], v[182:185], v[18:21]
	v_mfma_f32_16x16x32_bf16 v[10:13], v[150:153], v[190:193], v[10:13]
	v_mfma_f32_16x16x32_bf16 v[2:5], v[158:161], v[190:193], v[2:5]
	s_setprio 0
	s_barrier
	s_add_i32 s23, 0, 0x18000
	v_add_u32_e32 v0, s23, v247
	s_add_i32 s49, 0, 0x1c000
	ds_read_b128 v[130:133], v0
	ds_read_b128 v[134:137], v0 offset:1024
	ds_read_b128 v[138:141], v0 offset:2048
	ds_read_b128 v[142:145], v0 offset:3072
	v_add_u32_e32 v0, s49, v247
	ds_read_b128 v[146:149], v0
	ds_read_b128 v[150:153], v0 offset:1024
	ds_read_b128 v[154:157], v0 offset:2048
	ds_read_b128 v[158:161], v0 offset:3072
	s_add_u32 s38, s38, s86
	s_addc_u32 s39, s39, 0
	s_mov_b32 m0, s14
	v_lshl_add_u64 v[222:223], s[38:39], 0, v[196:197]
	ds_read_b128 v[162:165], v249 offset:32768
	ds_read_b128 v[166:169], v249 offset:33792
	ds_read_b128 v[170:173], v249 offset:34816
	ds_read_b128 v[174:177], v249 offset:35840
	ds_read_b128 v[178:181], v249 offset:36864
	ds_read_b128 v[182:185], v249 offset:37888
	ds_read_b128 v[186:189], v249 offset:38912
	ds_read_b128 v[190:193], v249 offset:39936
	global_load_lds_dwordx4 v[222:223], off
	v_lshl_add_u64 v[222:223], s[38:39], 0, v[200:201]
	s_mov_b32 m0, s15
	s_nop 0
	global_load_lds_dwordx4 v[222:223], off
	s_waitcnt vmcnt(8)
	s_waitcnt lgkmcnt(0)
	s_barrier
	s_setprio 1
	s_waitcnt lgkmcnt(0)
	v_mfma_f32_16x16x32_bf16 v[126:129], v[130:133], v[162:165], v[126:129]
	v_mfma_f32_16x16x32_bf16 v[118:121], v[138:141], v[162:165], v[118:121]
	v_mfma_f32_16x16x32_bf16 v[110:113], v[130:133], v[170:173], v[110:113]
	v_mfma_f32_16x16x32_bf16 v[102:105], v[138:141], v[170:173], v[102:105]
	v_mfma_f32_16x16x32_bf16 v[94:97], v[130:133], v[178:181], v[94:97]
	v_mfma_f32_16x16x32_bf16 v[86:89], v[138:141], v[178:181], v[86:89]
	v_mfma_f32_16x16x32_bf16 v[78:81], v[130:133], v[186:189], v[78:81]
	v_mfma_f32_16x16x32_bf16 v[70:73], v[138:141], v[186:189], v[70:73]
	v_mfma_f32_16x16x32_bf16 v[126:129], v[134:137], v[166:169], v[126:129]
	v_mfma_f32_16x16x32_bf16 v[118:121], v[142:145], v[166:169], v[118:121]
	v_mfma_f32_16x16x32_bf16 v[110:113], v[134:137], v[174:177], v[110:113]
	v_mfma_f32_16x16x32_bf16 v[102:105], v[142:145], v[174:177], v[102:105]
	v_mfma_f32_16x16x32_bf16 v[94:97], v[134:137], v[182:185], v[94:97]
	v_mfma_f32_16x16x32_bf16 v[86:89], v[142:145], v[182:185], v[86:89]
	v_mfma_f32_16x16x32_bf16 v[78:81], v[134:137], v[190:193], v[78:81]
	v_mfma_f32_16x16x32_bf16 v[70:73], v[142:145], v[190:193], v[70:73]
	s_setprio 0
	s_setprio 1
	v_mfma_f32_16x16x32_bf16 v[122:125], v[146:149], v[162:165], v[122:125]
	v_mfma_f32_16x16x32_bf16 v[114:117], v[154:157], v[162:165], v[114:117]
	v_mfma_f32_16x16x32_bf16 v[106:109], v[146:149], v[170:173], v[106:109]
	v_mfma_f32_16x16x32_bf16 v[98:101], v[154:157], v[170:173], v[98:101]
	v_mfma_f32_16x16x32_bf16 v[90:93], v[146:149], v[178:181], v[90:93]
	v_mfma_f32_16x16x32_bf16 v[82:85], v[154:157], v[178:181], v[82:85]
	v_mfma_f32_16x16x32_bf16 v[74:77], v[146:149], v[186:189], v[74:77]
	v_mfma_f32_16x16x32_bf16 v[66:69], v[154:157], v[186:189], v[66:69]
	v_mfma_f32_16x16x32_bf16 v[122:125], v[150:153], v[166:169], v[122:125]
	v_mfma_f32_16x16x32_bf16 v[114:117], v[158:161], v[166:169], v[114:117]
	v_mfma_f32_16x16x32_bf16 v[106:109], v[150:153], v[174:177], v[106:109]
	v_mfma_f32_16x16x32_bf16 v[98:101], v[158:161], v[174:177], v[98:101]
	v_mfma_f32_16x16x32_bf16 v[90:93], v[150:153], v[182:185], v[90:93]
	v_mfma_f32_16x16x32_bf16 v[82:85], v[158:161], v[182:185], v[82:85]
	v_mfma_f32_16x16x32_bf16 v[74:77], v[150:153], v[190:193], v[74:77]
	v_mfma_f32_16x16x32_bf16 v[66:69], v[158:161], v[190:193], v[66:69]
	s_setprio 0
	s_barrier
; #define PG8_STAGE(bufoff, gbase, voff) do { _Pragma("unroll") for (int _i = 0; _i < 2; ++_i) \
;         __builtin_amdgcn_global_load_lds((const unsigned*)((const char*)(gbase) + (voff)[_i]), (LAS unsigned*)(lds + (bufoff) + ldsw + _i * 8192), 16, 0, 0); } while (0)
; #define PG8_LDA(dst, b, h) do { _Pragma("unroll") for (int m = 0; m < 4; ++m) _Pragma("unroll") for (int k = 0; k < 2; ++k) dst[m][k] = *(const LAS bf16x8*)(lds + PG8_SA(b, h) + aoff + m * 2048 + k * 1024); } while (0)
; #define PG8_MMA(ai, bj, At, Bt) do { __builtin_amdgcn_s_setprio(1); _Pragma("unroll") for (int m = 0; m < 4; ++m) _Pragma("unroll") for (int n = 0; n < 2; ++n) _Pragma("unroll") for (int k = 0; k < 2; ++k) \
;         acc[ai][bj][m][n] = __builtin_amdgcn_mfma_f32_16x16x32_bf16(Bt[n][k], At[m][k], acc[ai][bj][m][n], 0, 0, 0); __builtin_amdgcn_s_setprio(0); } while (0)
; #define PG8_WAIT_V(n) asm volatile("s_waitcnt vmcnt(" #n ")" ::: "memory")
; #define PG8_WAIT_L(n) asm volatile("s_waitcnt lgkmcnt(" #n ")" ::: "memory")
; #define PG8_BAR __builtin_amdgcn_s_barrier()
; #define PG8_SCHED __builtin_amdgcn_sched_barrier(0)
; __device__ __forceinline__ void gemm_phase(LAS unsigned char* lds, const Gemm g, const StaticOrder& S, const LAS Epi* Ep, const int tid) {
;     ...
;             PG8_LDA(At, 1, 1); PG8_STAGE(PG8_SB(1, 0), b3, voffB); PG8_STAGE(PG8_SB(1, 1), b3 + hstepB, voffB); PG8_STAGE(PG8_SA(1, 0), a3, voffA);
;             PG8_WAIT_V(8); PG8_WAIT_L(0); PG8_BAR; PG8_MMA(1, 0, At, B0); PG8_MMA(1, 1, At, B1); PG8_BAR; PG8_SCHED;
;         }
	s_add_i32 s23, s23, s2
	v_lshl_add_u64 v[210:211], v[210:211], 0, s[88:89]
	s_mov_b32 m0, s23
	ds_read_b128 v[162:165], v249 offset:49152
	ds_read_b128 v[166:169], v249 offset:50176
	ds_read_b128 v[170:173], v249 offset:51200
	ds_read_b128 v[174:177], v249 offset:52224
	ds_read_b128 v[178:181], v249 offset:53248
	ds_read_b128 v[182:185], v249 offset:54272
	ds_read_b128 v[186:189], v249 offset:55296
	ds_read_b128 v[190:193], v249 offset:56320
	global_load_lds_dwordx4 v[210:211], off
	v_lshl_add_u64 v[210:211], v[212:213], 0, s[88:89]
	s_add_i32 m0, s23, 0x2000
	s_add_i32 s23, s49, s2
	global_load_lds_dwordx4 v[210:211], off
	v_lshl_add_u64 v[210:211], v[214:215], 0, s[88:89]
	s_mov_b32 m0, s23
	s_nop 0
	global_load_lds_dwordx4 v[210:211], off
	v_lshl_add_u64 v[210:211], v[216:217], 0, s[88:89]
	s_add_i32 m0, s23, 0x2000
	s_nop 0
	global_load_lds_dwordx4 v[210:211], off
	v_lshl_add_u64 v[210:211], v[218:219], 0, s[88:89]
	s_mov_b32 m0, s10
	s_nop 0
	global_load_lds_dwordx4 v[210:211], off
	v_lshl_add_u64 v[210:211], v[220:221], 0, s[88:89]
	s_mov_b32 m0, s11
	s_nop 0
	global_load_lds_dwordx4 v[210:211], off
	s_waitcnt vmcnt(8)
	s_waitcnt lgkmcnt(0)
	s_barrier
	s_setprio 1
	s_waitcnt lgkmcnt(0)
	v_mfma_f32_16x16x32_bf16 v[62:65], v[130:133], v[162:165], v[62:65]
	v_mfma_f32_16x16x32_bf16 v[54:57], v[138:141], v[162:165], v[54:57]
	v_mfma_f32_16x16x32_bf16 v[46:49], v[130:133], v[170:173], v[46:49]
	v_mfma_f32_16x16x32_bf16 v[38:41], v[138:141], v[170:173], v[38:41]
	v_mfma_f32_16x16x32_bf16 v[30:33], v[130:133], v[178:181], v[30:33]
	v_mfma_f32_16x16x32_bf16 v[22:25], v[138:141], v[178:181], v[22:25]
	v_mfma_f32_16x16x32_bf16 v[14:17], v[130:133], v[186:189], v[14:17]
	v_mfma_f32_16x16x32_bf16 v[6:9], v[138:141], v[186:189], v[6:9]
	v_mfma_f32_16x16x32_bf16 v[62:65], v[134:137], v[166:169], v[62:65]
	v_mfma_f32_16x16x32_bf16 v[54:57], v[142:145], v[166:169], v[54:57]
	v_mfma_f32_16x16x32_bf16 v[46:49], v[134:137], v[174:177], v[46:49]
	v_mfma_f32_16x16x32_bf16 v[38:41], v[142:145], v[174:177], v[38:41]
	v_mfma_f32_16x16x32_bf16 v[30:33], v[134:137], v[182:185], v[30:33]
	v_mfma_f32_16x16x32_bf16 v[22:25], v[142:145], v[182:185], v[22:25]
	v_mfma_f32_16x16x32_bf16 v[14:17], v[134:137], v[190:193], v[14:17]
	v_mfma_f32_16x16x32_bf16 v[6:9], v[142:145], v[190:193], v[6:9]
	s_setprio 0
	s_setprio 1
	v_mfma_f32_16x16x32_bf16 v[58:61], v[146:149], v[162:165], v[58:61]
	v_mfma_f32_16x16x32_bf16 v[50:53], v[154:157], v[162:165], v[50:53]
	v_mfma_f32_16x16x32_bf16 v[42:45], v[146:149], v[170:173], v[42:45]
	v_mfma_f32_16x16x32_bf16 v[34:37], v[154:157], v[170:173], v[34:37]
	v_mfma_f32_16x16x32_bf16 v[26:29], v[146:149], v[178:181], v[26:29]
	v_mfma_f32_16x16x32_bf16 v[18:21], v[154:157], v[178:181], v[18:21]
	v_mfma_f32_16x16x32_bf16 v[10:13], v[146:149], v[186:189], v[10:13]
	v_mfma_f32_16x16x32_bf16 v[2:5], v[154:157], v[186:189], v[2:5]
	v_mfma_f32_16x16x32_bf16 v[58:61], v[150:153], v[166:169], v[58:61]
	v_mfma_f32_16x16x32_bf16 v[50:53], v[158:161], v[166:169], v[50:53]
	v_mfma_f32_16x16x32_bf16 v[42:45], v[150:153], v[174:177], v[42:45]
	v_mfma_f32_16x16x32_bf16 v[34:37], v[158:161], v[174:177], v[34:37]
	v_mfma_f32_16x16x32_bf16 v[26:29], v[150:153], v[182:185], v[26:29]
	v_mfma_f32_16x16x32_bf16 v[18:21], v[158:161], v[182:185], v[18:21]
	v_mfma_f32_16x16x32_bf16 v[10:13], v[150:153], v[190:193], v[10:13]
	v_mfma_f32_16x16x32_bf16 v[2:5], v[158:161], v[190:193], v[2:5]
	s_setprio 0
	s_barrier
	s_add_u32 s0, s0, 0x100
	s_addc_u32 s1, s1, 0
	s_add_u32 s3, s3, 0x100
	s_addc_u32 s5, s5, 0
	s_cmp_ge_u32 s48, s16
	s_mov_b32 s23, s48
	s_cbranch_scc0 .LBB0_1434
	s_branch .Lpeel2_exit

; #define PG8_BAR __builtin_amdgcn_s_barrier()
; __device__ __forceinline__ void gemm_phase(LAS unsigned char* lds, const Gemm g, const StaticOrder& S, const LAS Epi* Ep, const int tid) {
;     ...
;         if (!has_next) break;
; #pragma unroll
;         for (int a = 0; a < 2; ++a)
; #pragma unroll
;             for (int b = 0; b < 2; ++b)
; #pragma unroll
;                 for (int m = 0; m < 4; ++m)
; #pragma unroll
;                     for (int n = 0; n < 2; ++n) acc[a][b][m][n] = (f32x4){0.f, 0.f, 0.f, 0.f};
;         cur = nxt; cA = nA; cB = nB; ++ui;
;         if (wr == 1) PG8_BAR;
.LBB0_1631:
	s_and_b64 vcc, exec, s[46:47]
	s_mov_b64 s[0:1], -1
	s_cbranch_vccnz .LBB0_1426
	s_mov_b32 s32, 0
	s_andn2_b64 vcc, exec, s[28:29]
	s_cbranch_vccnz .LBB0_1425
	s_mov_b32 s32, 1
	s_branch .LBB0_1425

; __device__ __forceinline__ unsigned xb_ld(unsigned* p)              { return __hip_atomic_load(p, __ATOMIC_RELAXED, __HIP_MEMORY_SCOPE_AGENT); }
; __device__ __forceinline__ unsigned xb_add(unsigned* p, unsigned v) { return __hip_atomic_fetch_add(p, v, __ATOMIC_RELAXED, __HIP_MEMORY_SCOPE_AGENT); }
; #define XB_SPIN(cond, bar) do { unsigned _sp = 0; while (cond) { __builtin_amdgcn_s_sleep(6); \
;     if ((++_sp & 255u) == 0u) { if (xb_ld(&(bar)[XB_TMO])) break; if (_sp > XB_SPIN_CAP) { atomicAdd(&(bar)[XB_TMO], 1u); break; } } } } while (0)
; __device__ __forceinline__ void xcd_barrier(const XcdBarrier& b) {
;     ...
;         const unsigned old = xb_add(&bar[XB_XSUB(b.x)], 1u);
;         const unsigned gen = old / nloc;
;         if (old + 1u == (gen + 1u) * nloc) {
;             __builtin_amdgcn_fence(__ATOMIC_RELEASE, "agent");
;             asm volatile("s_waitcnt vmcnt(0)" ::: "memory");
;             const unsigned og = xb_add(&bar[XB_TOP], 1u);
;             const unsigned tg = og / nx;
;             if (og + 1u == (tg + 1u) * nx) xb_add(&bar[XB_TOPGEN], 1u);
;             else XB_SPIN(xb_ld(&bar[XB_TOPGEN]) == tg, bar);
;             __builtin_amdgcn_fence(__ATOMIC_ACQUIRE, "agent");
;             xb_add(&bar[XB_XGEN(b.x)], 1u);
;             asm volatile("s_waitcnt vmcnt(0)" ::: "memory");
;         } else {
;             XB_SPIN(xb_ld(&bar[XB_XGEN(b.x)]) == gen, bar);
.LBB0_1690:
	s_or_b64 exec, exec, s[6:7]
	v_cvt_f32_u32_e32 v5, v3
	s_waitcnt vmcnt(0)
	v_readfirstlane_b32 s3, v4
	v_sub_u32_e32 v4, 0, v3
	v_rcp_iflag_f32_e32 v5, v5
	v_add_u32_e32 v6, s3, v0
	v_mul_f32_e32 v5, 0x4f7ffffe, v5
	v_cvt_u32_f32_e32 v5, v5
	v_mul_lo_u32 v0, v4, v5
	v_mul_hi_u32 v0, v5, v0
	v_add_u32_e32 v0, v5, v0
	v_mul_hi_u32 v0, v6, v0
	v_mul_lo_u32 v4, v0, v3
	v_sub_u32_e32 v4, v6, v4
	v_add_u32_e32 v5, 1, v0
	v_cmp_ge_u32_e32 vcc, v4, v3
	s_nop 1
	v_cndmask_b32_e32 v0, v0, v5, vcc
	v_sub_u32_e32 v5, v4, v3
	v_cndmask_b32_e32 v4, v4, v5, vcc
	v_add_u32_e32 v5, 1, v0
	v_cmp_ge_u32_e32 vcc, v4, v3
	v_add_u32_e32 v4, 1, v6
	s_nop 0
	v_cndmask_b32_e32 v0, v0, v5, vcc
	v_mul_lo_u32 v5, v3, v0
	v_add_u32_e32 v3, v5, v3
	v_cmp_ne_u32_e32 vcc, v4, v3
	s_and_saveexec_b64 s[6:7], vcc
	s_xor_b64 s[6:7], exec, s[6:7]
	s_cbranch_execz .LBB0_1704
	v_readlane_b32 s8, v252, 58
	v_readlane_b32 s9, v252, 59
	s_waitcnt lgkmcnt(0)
	s_nop 3
	global_load_dword v2, v1, s[8:9] sc1
	s_waitcnt vmcnt(0)
	v_cmp_eq_u32_e32 vcc, v2, v0
	s_and_saveexec_b64 s[8:9], vcc
	s_cbranch_execz .LBB0_1703
	s_mov_b32 s3, 1
	s_mov_b64 s[10:11], 0
	s_branch .LBB0_1694

; __device__ __forceinline__ unsigned xb_add(unsigned* p, unsigned v) { return __hip_atomic_fetch_add(p, v, __ATOMIC_RELAXED, __HIP_MEMORY_SCOPE_AGENT); }
; __device__ __forceinline__ void xcd_barrier(const XcdBarrier& b) {
;     ...
;             __builtin_amdgcn_fence(__ATOMIC_ACQUIRE, "agent");
;             xb_add(&bar[XB_XGEN(b.x)], 1u);
.LBB0_1721:
	s_or_b64 exec, exec, s[6:7]
	s_mov_b64 s[6:7], exec
	v_mbcnt_lo_u32_b32 v0, s6, 0
	v_mbcnt_hi_u32_b32 v0, s7, v0
	v_cmp_eq_u32_e32 vcc, 0, v0
	s_waitcnt vmcnt(0)
	buffer_inv sc1
	s_and_saveexec_b64 s[8:9], vcc
	s_cbranch_execz .LBB0_1723
	s_bcnt1_i32_b64 s3, s[6:7]
	v_readlane_b32 s6, v253, 60
	v_mov_b32_e32 v0, s3
	v_readlane_b32 s7, v253, 61
	s_nop 4
.LBB0_1723:
	s_or_b64 exec, exec, s[8:9]
	s_waitcnt vmcnt(0)

; __device__ __forceinline__ unsigned xb_add(unsigned* p, unsigned v) { return __hip_atomic_fetch_add(p, v, __ATOMIC_RELAXED, __HIP_MEMORY_SCOPE_AGENT); }
; __device__ __forceinline__ void xcd_barrier(const XcdBarrier& b) {
;     ...
;             __builtin_amdgcn_fence(__ATOMIC_ACQUIRE, "agent");
;             xb_add(&bar[XB_XGEN(b.x)], 1u);
.LBB0_1798:
	s_or_b64 exec, exec, s[6:7]
	s_mov_b64 s[6:7], exec
	v_mbcnt_lo_u32_b32 v0, s6, 0
	v_mbcnt_hi_u32_b32 v0, s7, v0
	v_cmp_eq_u32_e32 vcc, 0, v0
	s_waitcnt vmcnt(0)
	buffer_inv sc1
	s_and_saveexec_b64 s[8:9], vcc
	s_cbranch_execz .LBB0_1800
	s_bcnt1_i32_b64 s2, s[6:7]
	v_mov_b32_e32 v0, 0x2000
	v_mov_b32_e32 v1, s2
.LBB0_1800:
	s_or_b64 exec, exec, s[8:9]
	s_waitcnt vmcnt(0)

; #define PG8_STAGE(bufoff, gbase, voff) do { _Pragma("unroll") for (int _i = 0; _i < 2; ++_i) \
;         __builtin_amdgcn_global_load_lds((const unsigned*)((const char*)(gbase) + (voff)[_i]), (LAS unsigned*)(lds + (bufoff) + ldsw + _i * 8192), 16, 0, 0); } while (0)
; #define PG8_WAIT_V(n) asm volatile("s_waitcnt vmcnt(" #n ")" ::: "memory")
; #define PG8_BAR __builtin_amdgcn_s_barrier()
; __device__ __forceinline__ void gemm_phase(LAS unsigned char* lds, const Gemm g, const StaticOrder& S, const LAS Epi* Ep, const int tid) {
;     ...
;     PG8_STAGE(PG8_SB(0, 0), cB, voffB); PG8_STAGE(PG8_SB(0, 1), cB + hstepB, voffB); PG8_STAGE(PG8_SA(0, 0), cA, voffA); PG8_STAGE(PG8_SA(0, 1), cA + hstepA, voffA);
;     if (wr == 1) PG8_BAR;
;     PG8_WAIT_V(2); PG8_BAR;
;     PG8_STAGE(PG8_SB(1, 0), cB + kstep, voffB); PG8_STAGE(PG8_SA(1, 0), cA + kstep, voffA); PG8_STAGE(PG8_SB(1, 1), cB + hstepB + kstep, voffB);
;     PG8_WAIT_V(6); PG8_BAR;
.LBB0_1836:
	s_add_i32 m0, s87, 0x18000
	v_lshl_add_u64 v[4:5], v[4:5], 0, s[90:91]
	s_waitcnt vmcnt(2)
	s_barrier
	global_load_lds_dwordx4 v[4:5], off
	v_lshl_add_u64 v[4:5], v[6:7], 0, s[90:91]
	s_add_i32 m0, s87, 0x1a000
	s_add_i32 s89, s87, 0x8000
	global_load_lds_dwordx4 v[4:5], off
	v_lshl_add_u64 v[4:5], v[12:13], 0, s[90:91]
	s_mov_b32 m0, s89
	s_add_i32 s36, s87, 0xa000
	global_load_lds_dwordx4 v[4:5], off
	v_lshl_add_u64 v[4:5], v[14:15], 0, s[90:91]
	s_mov_b32 m0, s36
	v_and_b32_e32 v229, 15, v16
	global_load_lds_dwordx4 v[4:5], off
	s_add_i32 m0, s87, 0x1c000
	v_lshl_add_u64 v[4:5], v[8:9], 0, s[90:91]
	global_load_lds_dwordx4 v[4:5], off
	v_lshl_add_u64 v[4:5], v[10:11], 0, s[90:91]
	s_add_i32 m0, s87, 0x1e000
	s_lshr_b32 s70, s3, 6
	global_load_lds_dwordx4 v[4:5], off
	v_and_b32_e32 v4, 48, v16
	v_lshlrev_b32_e32 v5, 2, v16
	v_lshl_or_b32 v4, v229, 6, v4
	v_and_b32_e32 v5, 32, v5
	s_lshl_b32 s3, s5, 13
	v_bitop3_b32 v6, v4, s3, v5 bitop3:0xde
	s_lshl_b32 s3, s4, 5
	s_and_b32 s3, s3, 0x60
	s_lshl_b32 s69, s5, 6
	s_lshl_b32 s4, s3, 7
	s_add_i32 s68, s70, -2
	s_cmpk_lt_u32 s6, 0x100
	v_bitop3_b32 v230, s4, v4, v5 bitop3:0xf6
	v_and_b32_e32 v4, 63, v16
	s_cselect_b64 s[4:5], -1, 0
	s_and_b32 s6, s6, 0x7ffffc0
	v_cmp_gt_u32_e64 s[40:41], 16, v4
	v_or_b32_e32 v4, s6, v4
	s_lshl_b32 s71, s2, 2
	v_lshlrev_b32_e32 v231, 5, v4
	v_cvt_f32_ubyte0_e32 v4, s71
	v_rcp_iflag_f32_e32 v4, v4
	v_lshrrev_b32_e32 v5, 1, v16
	v_add_u32_e32 v2, v21, v2
	v_and_or_b32 v204, v5, 24, s3
	v_mul_f32_e32 v4, 0x4f7ffffe, v4
	v_cvt_u32_f32_e32 v4, v4
	s_lshl_b32 s60, s2, 3
	s_sub_i32 s2, 0, s71
	v_add_lshl_u32 v2, v2, v17, 1
	v_readfirstlane_b32 s3, v4
	s_waitcnt vmcnt(6)
	s_mul_i32 s2, s2, s3
	v_lshl_add_u64 v[206:207], s[58:59], 0, v[2:3]
	v_add_u32_e32 v2, v20, v18
	s_mul_hi_u32 s2, s3, s2
	v_add_lshl_u32 v2, v2, v19, 1
	v_cmp_lt_u32_e64 s[42:43], 12, v229
	v_add_u32_e32 v202, -13, v229
	v_mov_b32_e32 v203, v3
	v_cmp_gt_u32_e64 s[44:45], 16, v204
	s_mov_b32 s57, s59
	s_mov_b32 s66, 0
	s_add_i32 s29, s3, s2
	v_lshl_add_u64 v[208:209], s[58:59], 0, v[2:3]
	s_mov_b32 s73, -1
	v_add_u32_e32 v232, 0, v6
	s_barrier
	s_mov_b32 s32, 0
	s_branch .LBB0_1839

; #define PG8_STAGE(bufoff, gbase, voff) do { _Pragma("unroll") for (int _i = 0; _i < 2; ++_i) \
;         __builtin_amdgcn_global_load_lds((const unsigned*)((const char*)(gbase) + (voff)[_i]), (LAS unsigned*)(lds + (bufoff) + ldsw + _i * 8192), 16, 0, 0); } while (0)
; #define PG8_LDA(dst, b, h) do { _Pragma("unroll") for (int m = 0; m < 4; ++m) _Pragma("unroll") for (int k = 0; k < 2; ++k) dst[m][k] = *(const LAS bf16x8*)(lds + PG8_SA(b, h) + aoff + m * 2048 + k * 1024); } while (0)
; #define PG8_LDB(dst, b, h) do { _Pragma("unroll") for (int n = 0; n < 2; ++n) _Pragma("unroll") for (int k = 0; k < 2; ++k) dst[n][k] = *(const LAS bf16x8*)(lds + PG8_SB(b, h) + boff + n * 2048 + k * 1024); } while (0)
; #define PG8_MMA(ai, bj, At, Bt) do { __builtin_amdgcn_s_setprio(1); _Pragma("unroll") for (int m = 0; m < 4; ++m) _Pragma("unroll") for (int n = 0; n < 2; ++n) _Pragma("unroll") for (int k = 0; k < 2; ++k) \
;         acc[ai][bj][m][n] = __builtin_amdgcn_mfma_f32_16x16x32_bf16(Bt[n][k], At[m][k], acc[ai][bj][m][n], 0, 0, 0); __builtin_amdgcn_s_setprio(0); } while (0)
; #define PG8_WAIT_V(n) asm volatile("s_waitcnt vmcnt(" #n ")" ::: "memory")
; #define PG8_WAIT_L(n) asm volatile("s_waitcnt lgkmcnt(" #n ")" ::: "memory")
; __device__ __forceinline__ void gemm_phase(LAS unsigned char* lds, const Gemm g, const StaticOrder& S, const LAS Epi* Ep, const int tid) {
;     ...
;         const bool has_next = S.next(ui + 1, nxt);
;         const char* nA = has_next ? (const char*)g.A + (size_t)nxt.pm * tstepA : cA; const char* nB = has_next ? (const char*)g.Bt + (size_t)nxt.pn * tstepB : cB;
;         for (int t = 0; t < nt; t += 2) {
;             const bool last = (t == nt - 2);
;             const char* a1 = cA + (size_t)(t + 1) * kstep;
;             const char* a2 = last ? nA : cA + (size_t)(t + 2) * kstep; const char* b2 = last ? nB : cB + (size_t)(t + 2) * kstep;
;             const char* a3 = a2 + kstep; const char* b3 = b2 + kstep;
;             PG8_LDB(B0, 0, 0); PG8_LDB(B1, 0, 1); PG8_SCHED; PG8_LDA(At, 0, 0); PG8_STAGE(PG8_SA(1, 1), a1 + hstepA, voffA);
;             PG8_WAIT_V(8); PG8_WAIT_L(0); PG8_BAR; PG8_MMA(0, 0, At, B0); PG8_MMA(0, 1, At, B1); PG8_BAR; PG8_SCHED;
;             PG8_LDA(At, 0, 1); PG8_STAGE(PG8_SB(0, 0), b2, voffB); PG8_STAGE(PG8_SB(0, 1), b2 + hstepB, voffB); PG8_STAGE(PG8_SA(0, 0), a2, voffA);
;     ...
;         if (wr == 1) PG8_BAR;
.LBB0_1845:
	s_add_u32 s0, s0, 0x80
	s_addc_u32 s1, s1, 0
	s_add_u32 s3, s10, 0x100
	s_addc_u32 s12, s11, 0
	s_mov_b32 s10, 0
	s_cmp_eq_u32 s32, 0
	s_cbranch_scc1 .Lstag3_skip
	s_barrier
.Lstag3_skip:
	s_add_i32 s13, s10, 2
	s_add_u32 s14, s0, 0x80
	s_addc_u32 s11, s1, 0
	s_add_i32 s16, 0, 0x10000
	s_cmp_eq_u32 s68, s10
	s_cselect_b32 s11, s7, s11
	s_cselect_b32 s10, s6, s14
	v_add_u32_e32 v2, s16, v230
	s_cselect_b32 s15, s9, s12
	s_cselect_b32 s14, s8, s3
	s_add_i32 s17, 0, 0x14000
	s_waitcnt lgkmcnt(0)
	ds_read_b128 v[132:135], v2
	ds_read_b128 v[136:139], v2 offset:1024
	ds_read_b128 v[140:143], v2 offset:2048
	ds_read_b128 v[144:147], v2 offset:3072
	v_add_u32_e32 v2, s17, v230
	ds_read_b128 v[148:151], v2
	ds_read_b128 v[152:155], v2 offset:1024
	ds_read_b128 v[156:159], v2 offset:2048
	ds_read_b128 v[160:163], v2 offset:3072
	v_lshl_add_u64 v[210:211], s[0:1], 0, v[206:207]
	s_add_i32 m0, s87, 0xc000
	ds_read_b128 v[164:167], v232
	ds_read_b128 v[168:171], v232 offset:1024
	ds_read_b128 v[172:175], v232 offset:2048
	ds_read_b128 v[176:179], v232 offset:3072
	ds_read_b128 v[180:183], v232 offset:4096
	ds_read_b128 v[184:187], v232 offset:5120
	ds_read_b128 v[188:191], v232 offset:6144
	ds_read_b128 v[192:195], v232 offset:7168
	global_load_lds_dwordx4 v[210:211], off
	v_lshl_add_u64 v[210:211], s[0:1], 0, v[208:209]
	s_add_i32 m0, s87, 0xe000
	s_nop 0
	global_load_lds_dwordx4 v[210:211], off
	s_waitcnt vmcnt(8)
	s_waitcnt lgkmcnt(0)
	s_barrier
	s_setprio 1
	s_waitcnt lgkmcnt(0)
	v_mfma_f32_16x16x32_bf16 v[128:131], v[132:135], v[164:167], 0
	v_mfma_f32_16x16x32_bf16 v[120:123], v[140:143], v[164:167], 0
	v_mfma_f32_16x16x32_bf16 v[112:115], v[132:135], v[172:175], 0
	v_mfma_f32_16x16x32_bf16 v[104:107], v[140:143], v[172:175], 0
	v_mfma_f32_16x16x32_bf16 v[96:99], v[132:135], v[180:183], 0
	v_mfma_f32_16x16x32_bf16 v[88:91], v[140:143], v[180:183], 0
	v_mfma_f32_16x16x32_bf16 v[80:83], v[132:135], v[188:191], 0
	v_mfma_f32_16x16x32_bf16 v[72:75], v[140:143], v[188:191], 0
	v_mfma_f32_16x16x32_bf16 v[128:131], v[136:139], v[168:171], v[128:131]
	v_mfma_f32_16x16x32_bf16 v[120:123], v[144:147], v[168:171], v[120:123]
	v_mfma_f32_16x16x32_bf16 v[112:115], v[136:139], v[176:179], v[112:115]
	v_mfma_f32_16x16x32_bf16 v[104:107], v[144:147], v[176:179], v[104:107]
	v_mfma_f32_16x16x32_bf16 v[96:99], v[136:139], v[184:187], v[96:99]
	v_mfma_f32_16x16x32_bf16 v[88:91], v[144:147], v[184:187], v[88:91]
	v_mfma_f32_16x16x32_bf16 v[80:83], v[136:139], v[192:195], v[80:83]
	v_mfma_f32_16x16x32_bf16 v[72:75], v[144:147], v[192:195], v[72:75]
	s_setprio 0
	s_setprio 1
	v_mfma_f32_16x16x32_bf16 v[124:127], v[148:151], v[164:167], 0
	v_mfma_f32_16x16x32_bf16 v[116:119], v[156:159], v[164:167], 0
	v_mfma_f32_16x16x32_bf16 v[108:111], v[148:151], v[172:175], 0
	v_mfma_f32_16x16x32_bf16 v[100:103], v[156:159], v[172:175], 0
	v_mfma_f32_16x16x32_bf16 v[92:95], v[148:151], v[180:183], 0
	v_mfma_f32_16x16x32_bf16 v[84:87], v[156:159], v[180:183], 0
	v_mfma_f32_16x16x32_bf16 v[76:79], v[148:151], v[188:191], 0
	v_mfma_f32_16x16x32_bf16 v[68:71], v[156:159], v[188:191], 0
	v_mfma_f32_16x16x32_bf16 v[124:127], v[152:155], v[168:171], v[124:127]
	v_mfma_f32_16x16x32_bf16 v[116:119], v[160:163], v[168:171], v[116:119]
	v_mfma_f32_16x16x32_bf16 v[108:111], v[152:155], v[176:179], v[108:111]
	v_mfma_f32_16x16x32_bf16 v[100:103], v[160:163], v[176:179], v[100:103]
	v_mfma_f32_16x16x32_bf16 v[92:95], v[152:155], v[184:187], v[92:95]
	v_mfma_f32_16x16x32_bf16 v[84:87], v[160:163], v[184:187], v[84:87]
	v_mfma_f32_16x16x32_bf16 v[76:79], v[152:155], v[192:195], v[76:79]
	v_mfma_f32_16x16x32_bf16 v[68:71], v[160:163], v[192:195], v[68:71]
	s_setprio 0
	s_barrier
	s_add_i32 s16, s16, s86
	v_lshl_add_u64 v[210:211], s[14:15], 0, v[196:197]
	s_mov_b32 m0, s16
	ds_read_b128 v[164:167], v232 offset:16384
	ds_read_b128 v[168:171], v232 offset:17408
	ds_read_b128 v[172:175], v232 offset:18432
	ds_read_b128 v[176:179], v232 offset:19456
	ds_read_b128 v[180:183], v232 offset:20480
	ds_read_b128 v[184:187], v232 offset:21504
	ds_read_b128 v[188:191], v232 offset:22528
	ds_read_b128 v[192:195], v232 offset:23552
	global_load_lds_dwordx4 v[210:211], off
	s_add_i32 m0, s16, 0x2000
	v_lshl_add_u64 v[212:213], s[14:15], 0, v[200:201]
	s_add_u32 s14, s14, s58
	s_addc_u32 s15, s15, 0
	s_add_i32 s16, s17, s86
	global_load_lds_dwordx4 v[212:213], off
	v_lshl_add_u64 v[214:215], s[14:15], 0, v[196:197]
	s_mov_b32 m0, s16
	v_lshl_add_u64 v[216:217], s[14:15], 0, v[200:201]
	global_load_lds_dwordx4 v[214:215], off
	s_add_i32 m0, s16, 0x2000
	v_lshl_add_u64 v[218:219], s[10:11], 0, v[0:1]
	global_load_lds_dwordx4 v[216:217], off
	s_mov_b32 m0, s87
	v_lshl_add_u64 v[220:221], s[10:11], 0, v[198:199]
	global_load_lds_dwordx4 v[218:219], off
	s_mov_b32 m0, s38
	s_nop 0
	global_load_lds_dwordx4 v[220:221], off
	s_waitcnt vmcnt(8)
	s_waitcnt lgkmcnt(0)
	s_barrier
; #define PG8_STAGE(bufoff, gbase, voff) do { _Pragma("unroll") for (int _i = 0; _i < 2; ++_i) \
;         __builtin_amdgcn_global_load_lds((const unsigned*)((const char*)(gbase) + (voff)[_i]), (LAS unsigned*)(lds + (bufoff) + ldsw + _i * 8192), 16, 0, 0); } while (0)
; #define PG8_LDA(dst, b, h) do { _Pragma("unroll") for (int m = 0; m < 4; ++m) _Pragma("unroll") for (int k = 0; k < 2; ++k) dst[m][k] = *(const LAS bf16x8*)(lds + PG8_SA(b, h) + aoff + m * 2048 + k * 1024); } while (0)
; #define PG8_LDB(dst, b, h) do { _Pragma("unroll") for (int n = 0; n < 2; ++n) _Pragma("unroll") for (int k = 0; k < 2; ++k) dst[n][k] = *(const LAS bf16x8*)(lds + PG8_SB(b, h) + boff + n * 2048 + k * 1024); } while (0)
; #define PG8_MMA(ai, bj, At, Bt) do { __builtin_amdgcn_s_setprio(1); _Pragma("unroll") for (int m = 0; m < 4; ++m) _Pragma("unroll") for (int n = 0; n < 2; ++n) _Pragma("unroll") for (int k = 0; k < 2; ++k) \
;         acc[ai][bj][m][n] = __builtin_amdgcn_mfma_f32_16x16x32_bf16(Bt[n][k], At[m][k], acc[ai][bj][m][n], 0, 0, 0); __builtin_amdgcn_s_setprio(0); } while (0)
; #define PG8_WAIT_V(n) asm volatile("s_waitcnt vmcnt(" #n ")" ::: "memory")
; #define PG8_WAIT_L(n) asm volatile("s_waitcnt lgkmcnt(" #n ")" ::: "memory")
; #define PG8_BAR __builtin_amdgcn_s_barrier()
; #define PG8_SCHED __builtin_amdgcn_sched_barrier(0)
; __device__ __forceinline__ void gemm_phase(LAS unsigned char* lds, const Gemm g, const StaticOrder& S, const LAS Epi* Ep, const int tid) {
;     ...
;             PG8_WAIT_V(8); PG8_WAIT_L(0); PG8_BAR; PG8_MMA(1, 0, At, B0); PG8_MMA(1, 1, At, B1); PG8_BAR; PG8_SCHED;
;             PG8_LDB(B0, 1, 0); PG8_LDB(B1, 1, 1); PG8_SCHED; PG8_LDA(At, 1, 0); PG8_STAGE(PG8_SA(0, 1), a2 + hstepA, voffA);
;             PG8_WAIT_V(8); PG8_WAIT_L(0); PG8_BAR; PG8_MMA(0, 0, At, B0); PG8_MMA(0, 1, At, B1); PG8_BAR; PG8_SCHED;
	s_setprio 1
	s_waitcnt lgkmcnt(0)
	v_mfma_f32_16x16x32_bf16 v[64:67], v[132:135], v[164:167], 0
	v_mfma_f32_16x16x32_bf16 v[56:59], v[140:143], v[164:167], 0
	v_mfma_f32_16x16x32_bf16 v[48:51], v[132:135], v[172:175], 0
	v_mfma_f32_16x16x32_bf16 v[40:43], v[140:143], v[172:175], 0
	v_mfma_f32_16x16x32_bf16 v[32:35], v[132:135], v[180:183], 0
	v_mfma_f32_16x16x32_bf16 v[24:27], v[140:143], v[180:183], 0
	v_mfma_f32_16x16x32_bf16 v[16:19], v[132:135], v[188:191], 0
	v_mfma_f32_16x16x32_bf16 v[8:11], v[140:143], v[188:191], 0
	v_mfma_f32_16x16x32_bf16 v[64:67], v[136:139], v[168:171], v[64:67]
	v_mfma_f32_16x16x32_bf16 v[56:59], v[144:147], v[168:171], v[56:59]
	v_mfma_f32_16x16x32_bf16 v[48:51], v[136:139], v[176:179], v[48:51]
	v_mfma_f32_16x16x32_bf16 v[40:43], v[144:147], v[176:179], v[40:43]
	v_mfma_f32_16x16x32_bf16 v[32:35], v[136:139], v[184:187], v[32:35]
	v_mfma_f32_16x16x32_bf16 v[24:27], v[144:147], v[184:187], v[24:27]
	v_mfma_f32_16x16x32_bf16 v[16:19], v[136:139], v[192:195], v[16:19]
	v_mfma_f32_16x16x32_bf16 v[8:11], v[144:147], v[192:195], v[8:11]
	s_setprio 0
	s_setprio 1
	v_mfma_f32_16x16x32_bf16 v[60:63], v[148:151], v[164:167], 0
	v_mfma_f32_16x16x32_bf16 v[52:55], v[156:159], v[164:167], 0
	v_mfma_f32_16x16x32_bf16 v[44:47], v[148:151], v[172:175], 0
	v_mfma_f32_16x16x32_bf16 v[36:39], v[156:159], v[172:175], 0
	v_mfma_f32_16x16x32_bf16 v[28:31], v[148:151], v[180:183], 0
	v_mfma_f32_16x16x32_bf16 v[20:23], v[156:159], v[180:183], 0
	v_mfma_f32_16x16x32_bf16 v[12:15], v[148:151], v[188:191], 0
	v_mfma_f32_16x16x32_bf16 v[4:7], v[156:159], v[188:191], 0
	v_mfma_f32_16x16x32_bf16 v[60:63], v[152:155], v[168:171], v[60:63]
	v_mfma_f32_16x16x32_bf16 v[52:55], v[160:163], v[168:171], v[52:55]
	v_mfma_f32_16x16x32_bf16 v[44:47], v[152:155], v[176:179], v[44:47]
	v_mfma_f32_16x16x32_bf16 v[36:39], v[160:163], v[176:179], v[36:39]
	v_mfma_f32_16x16x32_bf16 v[28:31], v[152:155], v[184:187], v[28:31]
	v_mfma_f32_16x16x32_bf16 v[20:23], v[160:163], v[184:187], v[20:23]
	v_mfma_f32_16x16x32_bf16 v[12:15], v[152:155], v[192:195], v[12:15]
	v_mfma_f32_16x16x32_bf16 v[4:7], v[160:163], v[192:195], v[4:7]
	s_setprio 0
	s_barrier
	s_add_i32 s14, 0, 0x18000
	v_add_u32_e32 v2, s14, v230
	s_add_i32 s15, 0, 0x1c000
	ds_read_b128 v[132:135], v2
	ds_read_b128 v[136:139], v2 offset:1024
	ds_read_b128 v[140:143], v2 offset:2048
	ds_read_b128 v[144:147], v2 offset:3072
	v_add_u32_e32 v2, s15, v230
	ds_read_b128 v[148:151], v2
	ds_read_b128 v[152:155], v2 offset:1024
	ds_read_b128 v[156:159], v2 offset:2048
	ds_read_b128 v[160:163], v2 offset:3072
	s_add_u32 s10, s10, s58
	s_addc_u32 s11, s11, 0
	s_mov_b32 m0, s39
	v_lshl_add_u64 v[222:223], s[10:11], 0, v[0:1]
	ds_read_b128 v[164:167], v232 offset:32768
	ds_read_b128 v[168:171], v232 offset:33792
	ds_read_b128 v[172:175], v232 offset:34816
	ds_read_b128 v[176:179], v232 offset:35840
	ds_read_b128 v[180:183], v232 offset:36864
	ds_read_b128 v[184:187], v232 offset:37888
	ds_read_b128 v[188:191], v232 offset:38912
	ds_read_b128 v[192:195], v232 offset:39936
	global_load_lds_dwordx4 v[222:223], off
	v_lshl_add_u64 v[222:223], s[10:11], 0, v[198:199]
	s_mov_b32 m0, s88
	s_nop 0
	global_load_lds_dwordx4 v[222:223], off
	s_waitcnt vmcnt(8)
	s_waitcnt lgkmcnt(0)
	s_barrier
	s_setprio 1
	s_waitcnt lgkmcnt(0)
	v_mfma_f32_16x16x32_bf16 v[128:131], v[132:135], v[164:167], v[128:131]
	v_mfma_f32_16x16x32_bf16 v[120:123], v[140:143], v[164:167], v[120:123]
	v_mfma_f32_16x16x32_bf16 v[112:115], v[132:135], v[172:175], v[112:115]
	v_mfma_f32_16x16x32_bf16 v[104:107], v[140:143], v[172:175], v[104:107]
	v_mfma_f32_16x16x32_bf16 v[96:99], v[132:135], v[180:183], v[96:99]
	v_mfma_f32_16x16x32_bf16 v[88:91], v[140:143], v[180:183], v[88:91]
	v_mfma_f32_16x16x32_bf16 v[80:83], v[132:135], v[188:191], v[80:83]
	v_mfma_f32_16x16x32_bf16 v[72:75], v[140:143], v[188:191], v[72:75]
	v_mfma_f32_16x16x32_bf16 v[128:131], v[136:139], v[168:171], v[128:131]
	v_mfma_f32_16x16x32_bf16 v[120:123], v[144:147], v[168:171], v[120:123]
	v_mfma_f32_16x16x32_bf16 v[112:115], v[136:139], v[176:179], v[112:115]
	v_mfma_f32_16x16x32_bf16 v[104:107], v[144:147], v[176:179], v[104:107]
	v_mfma_f32_16x16x32_bf16 v[96:99], v[136:139], v[184:187], v[96:99]
	v_mfma_f32_16x16x32_bf16 v[88:91], v[144:147], v[184:187], v[88:91]
	v_mfma_f32_16x16x32_bf16 v[80:83], v[136:139], v[192:195], v[80:83]
	v_mfma_f32_16x16x32_bf16 v[72:75], v[144:147], v[192:195], v[72:75]
	s_setprio 0
	s_setprio 1
	v_mfma_f32_16x16x32_bf16 v[124:127], v[148:151], v[164:167], v[124:127]
	v_mfma_f32_16x16x32_bf16 v[116:119], v[156:159], v[164:167], v[116:119]
	v_mfma_f32_16x16x32_bf16 v[108:111], v[148:151], v[172:175], v[108:111]
	v_mfma_f32_16x16x32_bf16 v[100:103], v[156:159], v[172:175], v[100:103]
	v_mfma_f32_16x16x32_bf16 v[92:95], v[148:151], v[180:183], v[92:95]
	v_mfma_f32_16x16x32_bf16 v[84:87], v[156:159], v[180:183], v[84:87]
	v_mfma_f32_16x16x32_bf16 v[76:79], v[148:151], v[188:191], v[76:79]
	v_mfma_f32_16x16x32_bf16 v[68:71], v[156:159], v[188:191], v[68:71]
	v_mfma_f32_16x16x32_bf16 v[124:127], v[152:155], v[168:171], v[124:127]
	v_mfma_f32_16x16x32_bf16 v[116:119], v[160:163], v[168:171], v[116:119]
	v_mfma_f32_16x16x32_bf16 v[108:111], v[152:155], v[176:179], v[108:111]
	v_mfma_f32_16x16x32_bf16 v[100:103], v[160:163], v[176:179], v[100:103]
	v_mfma_f32_16x16x32_bf16 v[92:95], v[152:155], v[184:187], v[92:95]
	v_mfma_f32_16x16x32_bf16 v[84:87], v[160:163], v[184:187], v[84:87]
	v_mfma_f32_16x16x32_bf16 v[76:79], v[152:155], v[192:195], v[76:79]
	v_mfma_f32_16x16x32_bf16 v[68:71], v[160:163], v[192:195], v[68:71]
	s_setprio 0
	s_barrier
; #define PG8_STAGE(bufoff, gbase, voff) do { _Pragma("unroll") for (int _i = 0; _i < 2; ++_i) \
;         __builtin_amdgcn_global_load_lds((const unsigned*)((const char*)(gbase) + (voff)[_i]), (LAS unsigned*)(lds + (bufoff) + ldsw + _i * 8192), 16, 0, 0); } while (0)
; #define PG8_LDA(dst, b, h) do { _Pragma("unroll") for (int m = 0; m < 4; ++m) _Pragma("unroll") for (int k = 0; k < 2; ++k) dst[m][k] = *(const LAS bf16x8*)(lds + PG8_SA(b, h) + aoff + m * 2048 + k * 1024); } while (0)
; #define PG8_MMA(ai, bj, At, Bt) do { __builtin_amdgcn_s_setprio(1); _Pragma("unroll") for (int m = 0; m < 4; ++m) _Pragma("unroll") for (int n = 0; n < 2; ++n) _Pragma("unroll") for (int k = 0; k < 2; ++k) \
;         acc[ai][bj][m][n] = __builtin_amdgcn_mfma_f32_16x16x32_bf16(Bt[n][k], At[m][k], acc[ai][bj][m][n], 0, 0, 0); __builtin_amdgcn_s_setprio(0); } while (0)
; #define PG8_WAIT_V(n) asm volatile("s_waitcnt vmcnt(" #n ")" ::: "memory")
; #define PG8_WAIT_L(n) asm volatile("s_waitcnt lgkmcnt(" #n ")" ::: "memory")
; #define PG8_BAR __builtin_amdgcn_s_barrier()
; #define PG8_SCHED __builtin_amdgcn_sched_barrier(0)
; __device__ __forceinline__ void gemm_phase(LAS unsigned char* lds, const Gemm g, const StaticOrder& S, const LAS Epi* Ep, const int tid) {
;     ...
;             PG8_LDA(At, 1, 1); PG8_STAGE(PG8_SB(1, 0), b3, voffB); PG8_STAGE(PG8_SB(1, 1), b3 + hstepB, voffB); PG8_STAGE(PG8_SA(1, 0), a3, voffA);
;             PG8_WAIT_V(8); PG8_WAIT_L(0); PG8_BAR; PG8_MMA(1, 0, At, B0); PG8_MMA(1, 1, At, B1); PG8_BAR; PG8_SCHED;
;         }
	s_add_i32 s10, s14, s86
	v_lshl_add_u64 v[210:211], v[210:211], 0, s[90:91]
	s_mov_b32 m0, s10
	ds_read_b128 v[164:167], v232 offset:49152
	ds_read_b128 v[168:171], v232 offset:50176
	ds_read_b128 v[172:175], v232 offset:51200
	ds_read_b128 v[176:179], v232 offset:52224
	ds_read_b128 v[180:183], v232 offset:53248
	ds_read_b128 v[184:187], v232 offset:54272
	ds_read_b128 v[188:191], v232 offset:55296
	ds_read_b128 v[192:195], v232 offset:56320
	global_load_lds_dwordx4 v[210:211], off
	v_lshl_add_u64 v[210:211], v[212:213], 0, s[90:91]
	s_add_i32 m0, s10, 0x2000
	s_add_i32 s10, s15, s86
	global_load_lds_dwordx4 v[210:211], off
	v_lshl_add_u64 v[210:211], v[214:215], 0, s[90:91]
	s_mov_b32 m0, s10
	s_nop 0
	global_load_lds_dwordx4 v[210:211], off
	v_lshl_add_u64 v[210:211], v[216:217], 0, s[90:91]
	s_add_i32 m0, s10, 0x2000
	s_nop 0
	global_load_lds_dwordx4 v[210:211], off
	v_lshl_add_u64 v[210:211], v[218:219], 0, s[90:91]
	s_mov_b32 m0, s89
	s_nop 0
	global_load_lds_dwordx4 v[210:211], off
	v_lshl_add_u64 v[210:211], v[220:221], 0, s[90:91]
	s_mov_b32 m0, s36
	s_nop 0
	global_load_lds_dwordx4 v[210:211], off
	s_waitcnt vmcnt(8)
	s_waitcnt lgkmcnt(0)
	s_barrier
	s_setprio 1
	s_waitcnt lgkmcnt(0)
	v_mfma_f32_16x16x32_bf16 v[64:67], v[132:135], v[164:167], v[64:67]
	v_mfma_f32_16x16x32_bf16 v[56:59], v[140:143], v[164:167], v[56:59]
	v_mfma_f32_16x16x32_bf16 v[48:51], v[132:135], v[172:175], v[48:51]
	v_mfma_f32_16x16x32_bf16 v[40:43], v[140:143], v[172:175], v[40:43]
	v_mfma_f32_16x16x32_bf16 v[32:35], v[132:135], v[180:183], v[32:35]
	v_mfma_f32_16x16x32_bf16 v[24:27], v[140:143], v[180:183], v[24:27]
	v_mfma_f32_16x16x32_bf16 v[16:19], v[132:135], v[188:191], v[16:19]
	v_mfma_f32_16x16x32_bf16 v[8:11], v[140:143], v[188:191], v[8:11]
	v_mfma_f32_16x16x32_bf16 v[64:67], v[136:139], v[168:171], v[64:67]
	v_mfma_f32_16x16x32_bf16 v[56:59], v[144:147], v[168:171], v[56:59]
	v_mfma_f32_16x16x32_bf16 v[48:51], v[136:139], v[176:179], v[48:51]
	v_mfma_f32_16x16x32_bf16 v[40:43], v[144:147], v[176:179], v[40:43]
	v_mfma_f32_16x16x32_bf16 v[32:35], v[136:139], v[184:187], v[32:35]
	v_mfma_f32_16x16x32_bf16 v[24:27], v[144:147], v[184:187], v[24:27]
	v_mfma_f32_16x16x32_bf16 v[16:19], v[136:139], v[192:195], v[16:19]
	v_mfma_f32_16x16x32_bf16 v[8:11], v[144:147], v[192:195], v[8:11]
	s_setprio 0
	s_setprio 1
	v_mfma_f32_16x16x32_bf16 v[60:63], v[148:151], v[164:167], v[60:63]
	v_mfma_f32_16x16x32_bf16 v[52:55], v[156:159], v[164:167], v[52:55]
	v_mfma_f32_16x16x32_bf16 v[44:47], v[148:151], v[172:175], v[44:47]
	v_mfma_f32_16x16x32_bf16 v[36:39], v[156:159], v[172:175], v[36:39]
	v_mfma_f32_16x16x32_bf16 v[28:31], v[148:151], v[180:183], v[28:31]
	v_mfma_f32_16x16x32_bf16 v[20:23], v[156:159], v[180:183], v[20:23]
	v_mfma_f32_16x16x32_bf16 v[12:15], v[148:151], v[188:191], v[12:15]
	v_mfma_f32_16x16x32_bf16 v[4:7], v[156:159], v[188:191], v[4:7]
	v_mfma_f32_16x16x32_bf16 v[60:63], v[152:155], v[168:171], v[60:63]
	v_mfma_f32_16x16x32_bf16 v[52:55], v[160:163], v[168:171], v[52:55]
	v_mfma_f32_16x16x32_bf16 v[44:47], v[152:155], v[176:179], v[44:47]
	v_mfma_f32_16x16x32_bf16 v[36:39], v[160:163], v[176:179], v[36:39]
	v_mfma_f32_16x16x32_bf16 v[28:31], v[152:155], v[184:187], v[28:31]
	v_mfma_f32_16x16x32_bf16 v[20:23], v[160:163], v[184:187], v[20:23]
	v_mfma_f32_16x16x32_bf16 v[12:15], v[152:155], v[192:195], v[12:15]
	v_mfma_f32_16x16x32_bf16 v[4:7], v[160:163], v[192:195], v[4:7]
	s_setprio 0
	s_barrier
	s_add_u32 s0, s0, 0x100
	s_addc_u32 s1, s1, 0
	s_add_u32 s3, s3, 0x100
	s_addc_u32 s12, s12, 0
	s_cmp_ge_u32 s13, s70
	s_mov_b32 s10, s13
	s_cbranch_scc0 .LBB0_1846
	s_branch .Lpeel3_exit

; #define PG8_BAR __builtin_amdgcn_s_barrier()
; __device__ __forceinline__ void gemm_phase(LAS unsigned char* lds, const Gemm g, const StaticOrder& S, const LAS Epi* Ep, const int tid) {
;     ...
;         if (!has_next) break;
; #pragma unroll
;         for (int a = 0; a < 2; ++a)
; #pragma unroll
;             for (int b = 0; b < 2; ++b)
; #pragma unroll
;                 for (int m = 0; m < 4; ++m)
; #pragma unroll
;                     for (int n = 0; n < 2; ++n) acc[a][b][m][n] = (f32x4){0.f, 0.f, 0.f, 0.f};
;         cur = nxt; cA = nA; cB = nB; ++ui;
;         if (wr == 1) PG8_BAR;
.LBB0_2081:
	s_and_b64 vcc, exec, s[46:47]
	s_mov_b64 s[0:1], -1
	s_cbranch_vccnz .LBB0_1838
	s_mov_b32 s32, 0
	s_andn2_b64 vcc, exec, s[96:97]
	s_cbranch_vccnz .LBB0_1837
	s_mov_b32 s32, 1
	s_branch .LBB0_1837

; __device__ __forceinline__ unsigned xb_ld(unsigned* p)              { return __hip_atomic_load(p, __ATOMIC_RELAXED, __HIP_MEMORY_SCOPE_AGENT); }
; __device__ __forceinline__ unsigned xb_add(unsigned* p, unsigned v) { return __hip_atomic_fetch_add(p, v, __ATOMIC_RELAXED, __HIP_MEMORY_SCOPE_AGENT); }
; #define XB_SPIN(cond, bar) do { unsigned _sp = 0; while (cond) { __builtin_amdgcn_s_sleep(6); \
;     if ((++_sp & 255u) == 0u) { if (xb_ld(&(bar)[XB_TMO])) break; if (_sp > XB_SPIN_CAP) { atomicAdd(&(bar)[XB_TMO], 1u); break; } } } } while (0)
; __device__ __forceinline__ void xcd_barrier(const XcdBarrier& b) {
;     ...
;         const unsigned old = xb_add(&bar[XB_XSUB(b.x)], 1u);
;         const unsigned gen = old / nloc;
;         if (old + 1u == (gen + 1u) * nloc) {
;             __builtin_amdgcn_fence(__ATOMIC_RELEASE, "agent");
;             asm volatile("s_waitcnt vmcnt(0)" ::: "memory");
;             const unsigned og = xb_add(&bar[XB_TOP], 1u);
;             const unsigned tg = og / nx;
;             if (og + 1u == (tg + 1u) * nx) xb_add(&bar[XB_TOPGEN], 1u);
;             else XB_SPIN(xb_ld(&bar[XB_TOPGEN]) == tg, bar);
;             __builtin_amdgcn_fence(__ATOMIC_ACQUIRE, "agent");
;             xb_add(&bar[XB_XGEN(b.x)], 1u);
;             asm volatile("s_waitcnt vmcnt(0)" ::: "memory");
;         } else {
;             XB_SPIN(xb_ld(&bar[XB_XGEN(b.x)]) == gen, bar);
.LBB0_2140:
	s_or_b64 exec, exec, s[6:7]
	v_cvt_f32_u32_e32 v5, v2
	s_waitcnt vmcnt(0)
	v_readfirstlane_b32 s3, v4
	v_sub_u32_e32 v4, 0, v2
	v_rcp_iflag_f32_e32 v5, v5
	v_add_u32_e32 v6, s3, v1
	v_mul_f32_e32 v5, 0x4f7ffffe, v5
	v_cvt_u32_f32_e32 v5, v5
	v_mul_lo_u32 v1, v4, v5
	v_mul_hi_u32 v1, v5, v1
	v_add_u32_e32 v1, v5, v1
	v_mul_hi_u32 v1, v6, v1
	v_mul_lo_u32 v4, v1, v2
	v_sub_u32_e32 v4, v6, v4
	v_add_u32_e32 v5, 1, v1
	v_cmp_ge_u32_e32 vcc, v4, v2
	s_nop 1
	v_cndmask_b32_e32 v1, v1, v5, vcc
	v_sub_u32_e32 v5, v4, v2
	v_cndmask_b32_e32 v4, v4, v5, vcc
	v_add_u32_e32 v5, 1, v1
	v_cmp_ge_u32_e32 vcc, v4, v2
	v_add_u32_e32 v4, 1, v6
	s_nop 0
	v_cndmask_b32_e32 v1, v1, v5, vcc
	v_mul_lo_u32 v5, v2, v1
	v_add_u32_e32 v2, v5, v2
	v_cmp_ne_u32_e32 vcc, v4, v2
	s_and_saveexec_b64 s[6:7], vcc
	s_xor_b64 s[6:7], exec, s[6:7]
	s_cbranch_execz .LBB0_2154
	v_readlane_b32 s8, v252, 3
	v_readlane_b32 s9, v252, 4
	s_waitcnt lgkmcnt(0)
	s_nop 3
	global_load_dword v0, v3, s[8:9] sc1
	s_waitcnt vmcnt(0)
	v_cmp_eq_u32_e32 vcc, v0, v1
	s_and_saveexec_b64 s[8:9], vcc
	s_cbranch_execz .LBB0_2153
	s_mov_b32 s3, 1
	s_mov_b64 s[10:11], 0
	s_branch .LBB0_2144

; __device__ __forceinline__ unsigned xb_ld(unsigned* p)              { return __hip_atomic_load(p, __ATOMIC_RELAXED, __HIP_MEMORY_SCOPE_AGENT); }
; #define XB_SPIN(cond, bar) do { unsigned _sp = 0; while (cond) { __builtin_amdgcn_s_sleep(6); \
;     if ((++_sp & 255u) == 0u) { if (xb_ld(&(bar)[XB_TMO])) break; if (_sp > XB_SPIN_CAP) { atomicAdd(&(bar)[XB_TMO], 1u); break; } } } } while (0)
; __device__ __forceinline__ void xcd_barrier(const XcdBarrier& b) {
;     ...
;             XB_SPIN(xb_ld(&bar[XB_XGEN(b.x)]) == gen, bar);
;             __builtin_amdgcn_fence(__ATOMIC_ACQUIRE, "agent");
.LBB0_2146:
	v_readlane_b32 s14, v252, 3
	v_readlane_b32 s15, v252, 4
	s_add_i32 s3, s3, 1
	s_mov_b64 s[16:17], -1
	s_nop 2
	global_load_dword v0, v3, s[14:15] sc1
	s_waitcnt vmcnt(0)
	v_cmp_ne_u32_e32 vcc, v0, v1
	s_orn2_b64 s[14:15], vcc, exec
	s_branch .LBB0_2143

; __device__ __forceinline__ unsigned xb_add(unsigned* p, unsigned v) { return __hip_atomic_fetch_add(p, v, __ATOMIC_RELAXED, __HIP_MEMORY_SCOPE_AGENT); }
; __device__ __forceinline__ void xcd_barrier(const XcdBarrier& b) {
;     ...
;             __builtin_amdgcn_fence(__ATOMIC_ACQUIRE, "agent");
;             xb_add(&bar[XB_XGEN(b.x)], 1u);
.LBB0_2171:
	s_or_b64 exec, exec, s[6:7]
	s_mov_b64 s[6:7], exec
	v_mbcnt_lo_u32_b32 v0, s6, 0
	v_mbcnt_hi_u32_b32 v0, s7, v0
	v_cmp_eq_u32_e32 vcc, 0, v0
	s_waitcnt vmcnt(0)
	buffer_inv sc1
	s_and_saveexec_b64 s[8:9], vcc
	s_cbranch_execz .LBB0_2173
	s_bcnt1_i32_b64 s3, s[6:7]
	v_readlane_b32 s6, v253, 58
	v_mov_b32_e32 v0, s3
	v_readlane_b32 s7, v253, 59
	s_nop 4
.LBB0_2173:
	s_or_b64 exec, exec, s[8:9]
	s_waitcnt vmcnt(0)
